# v38 + pipelined GEMM K-loops with waves 4-7 staggered by half a K-step (barrier+DMA at step start)
# speedup vs baseline: 1.0173x; 1.0032x over previous
; template <int MODE, bool SWAP, int MT>
; DI void gemm_tile(const int wv_, const Params& p, const u16* __restrict__ A, const u16* __restrict__ Bt, int brow, int bcol, char* smem, const float* gnext) {
;     ...
;   const int tid = tid_, wid = tid >> 6, lane = tid & 63, wr = wid >> 1, wc = wid & 1, fr = lane & 15, fq = lane >> 4;
;   f32x4 acc[MT][4];
; #pragma unroll
;   for (int m = 0; m < MT; ++m)
; #pragma unroll
;     for (int n = 0; n < 4; ++n) acc[m][n] = f32x4{0.f, 0.f, 0.f, 0.f};
;   const int ra = tid >> 2, cb = (tid & 3) * 8;
;   const u16* ga0 = A + (size_t)(brow + ra) * 1024 + cb;
;   const u16* ga1 = A + (size_t)(brow + 128 + ra) * 1024 + cb;
;   const u16* gb0 = Bt + (size_t)(bcol + ra) * 1024 + cb;
;   auto stage = [&](int t, int buf) {
;     char* sA = smem + buf * 24576; char* sB = sA + 16384;
;     if (MT >= 2 || tid < 256) __builtin_amdgcn_global_load_lds((const unsigned*)(ga0 + t * 32), (unsigned*)(sA + tid * 16), 16, 0, 0);
;     if (MT == 4) __builtin_amdgcn_global_load_lds((const unsigned*)(ga1 + t * 32), (unsigned*)(sA + 8192 + tid * 16), 16, 0, 0);
;     __builtin_amdgcn_global_load_lds((const unsigned*)(gb0 + t * 32), (unsigned*)(sB + tid * 16), 16, 0, 0);
;   };
;   stage(0, 0);
;   for (int t = 0; t < 32; ++t) {
;     asm volatile("s_waitcnt vmcnt(0)" ::: "memory");
;     __syncthreads();
;     if (t + 1 < 32) stage(t + 1, (t + 1) & 1);
;     const char* sA = smem + (t & 1) * 24576; const char* sB = sA + 16384;
;     bf16x8 Af[MT], Bf[4];
; #pragma unroll
;     for (int n = 0; n < 4; ++n) Bf[n] = *(const bf16x8*)(sB + (wc * 64 + n * 16 + fr) * 64 + fq * 16);
;     constexpr int MH = MT >= 2 ? MT / 2 : 1;
; #pragma unroll
;     for (int m = 0; m < MH; ++m) Af[m] = *(const bf16x8*)(sA + (wr * (16 * MT) + m * 16 + fr) * 64 + fq * 16);
.LBB0_84:
	s_mul_hi_i32 s0, s14, 0x92492493
	s_add_i32 s0, s0, s14
	s_lshr_b32 s1, s0, 31
	s_ashr_i32 s0, s0, 4
	s_add_i32 s19, s0, s1
	s_mul_i32 s0, s19, 0xffffffe4
	s_add_i32 s0, s0, s14
	s_and_b32 s1, s0, -4
	s_lshl_b32 s18, s19, 8
	s_lshl_b32 s15, s0, 7
	s_cmp_lg_u32 s1, 20
	s_mov_b64 s[0:1], -1
	s_mulk_i32 s19, 0xe00
	s_cbranch_scc0 .LBB0_88
	s_mov_b32 s1, 0
	v_readlane_b32 s20, v127, 0
	v_mbcnt_lo_u32_b32 v0, -1, s1
	v_mbcnt_hi_u32_b32 v0, -1, v0
	v_add_u32_e32 v12, s33, v0
	s_mov_b32 s1, s16
	v_ashrrev_i32_e32 v13, 2, v12
	v_add_u32_e32 v0, s18, v13
	s_mov_b32 s1, s17
	v_ashrrev_i32_e32 v1, 31, v0
	v_lshlrev_b64 v[4:5], 11, v[0:1]
	v_readlane_b32 s21, v127, 1
	v_lshlrev_b32_e32 v76, 4, v12
	v_and_b32_e32 v2, 48, v76
	v_lshl_add_u64 v[6:7], s[20:21], 0, v[4:5]
	v_add_u32_e32 v0, 0x80, v0
	v_readfirstlane_b32 s1, v76
	v_lshl_add_u64 v[6:7], v[6:7], 0, v[2:3]
	v_ashrrev_i32_e32 v1, 31, v0
	s_mov_b32 m0, s1
	v_lshlrev_b64 v[8:9], 11, v[0:1]
	global_load_lds_dwordx4 v[6:7], off
	v_add_u32_e32 v6, 0x2000, v76
	v_lshl_add_u64 v[0:1], s[20:21], 0, v[8:9]
	v_add_u32_e32 v10, s15, v13
	v_readfirstlane_b32 s1, v6
	v_lshl_add_u64 v[0:1], v[0:1], 0, v[2:3]
	v_ashrrev_i32_e32 v11, 31, v10
	s_mov_b32 m0, s1
	v_lshlrev_b64 v[10:11], 11, v[10:11]
	global_load_lds_dwordx4 v[0:1], off
	v_add_u32_e32 v0, 0x4000, v76
	v_lshl_add_u64 v[10:11], s[2:3], 0, v[10:11]
	v_readfirstlane_b32 s1, v0
	v_lshl_add_u64 v[10:11], v[10:11], 0, v[2:3]
	s_mov_b32 m0, s1
	v_and_b32_e32 v74, 15, v12
	global_load_lds_dwordx4 v[10:11], off
	v_readlane_b32 s20, v127, 22
	v_bfe_u32 v72, v12, 6, 1
	v_ashrrev_i32_e32 v73, 7, v12
	v_lshlrev_b32_e32 v0, 6, v74
	v_or_b32_e32 v4, v4, v2
	v_readlane_b32 s21, v127, 23
	v_lshl_or_b32 v78, v72, 12, v0
	v_lshl_or_b32 v79, v73, 12, v0
	v_lshl_add_u64 v[0:1], s[20:21], 0, v[4:5]
	v_add_u32_e32 v4, s12, v13
	v_subrev_u32_e32 v4, s19, v4
	v_ashrrev_i32_e32 v5, 31, v4
	v_lshlrev_b64 v[4:5], 11, v[4:5]
	v_or_b32_e32 v4, v4, v2
	v_bfe_u32 v75, v12, 4, 2
	v_or_b32_e32 v8, v8, v2
	v_lshl_add_u64 v[70:71], s[4:5], 0, v[4:5]
	v_mov_b32_e32 v4, 0
	s_mov_b32 s0, 0
	v_lshlrev_b32_e32 v77, 4, v75
	v_lshl_add_u64 v[68:69], s[20:21], 0, v[8:9]
	v_mov_b32_e32 v5, v4
	v_mov_b32_e32 v6, v4
	v_mov_b32_e32 v7, v4
	v_mov_b32_e32 v8, v4
	v_mov_b32_e32 v9, v4
	v_mov_b32_e32 v10, v4
	v_mov_b32_e32 v11, v4
	v_mov_b32_e32 v12, v4
	v_mov_b32_e32 v13, v4
	v_mov_b32_e32 v14, v4
	v_mov_b32_e32 v15, v4
	v_mov_b32_e32 v16, v4
	v_mov_b32_e32 v17, v4
	v_mov_b32_e32 v18, v4
	v_mov_b32_e32 v19, v4
	v_mov_b32_e32 v20, v4
	v_mov_b32_e32 v21, v4
	v_mov_b32_e32 v22, v4
	v_mov_b32_e32 v23, v4
	v_mov_b32_e32 v24, v4
	v_mov_b32_e32 v25, v4
	v_mov_b32_e32 v26, v4
	v_mov_b32_e32 v27, v4
	v_mov_b32_e32 v28, v4
	v_mov_b32_e32 v29, v4
	v_mov_b32_e32 v30, v4
	v_mov_b32_e32 v31, v4
	v_mov_b32_e32 v32, v4
	v_mov_b32_e32 v33, v4
	v_mov_b32_e32 v34, v4
	v_mov_b32_e32 v35, v4
	v_mov_b32_e32 v44, v4
	v_mov_b32_e32 v45, v4
	v_mov_b32_e32 v46, v4
	v_mov_b32_e32 v47, v4
	v_mov_b32_e32 v36, v4
	v_mov_b32_e32 v37, v4
	v_mov_b32_e32 v38, v4
	v_mov_b32_e32 v39, v4
	v_mov_b32_e32 v40, v4
	v_mov_b32_e32 v41, v4
	v_mov_b32_e32 v42, v4
	v_mov_b32_e32 v43, v4
	v_mov_b32_e32 v48, v4
	v_mov_b32_e32 v49, v4
	v_mov_b32_e32 v50, v4
	v_mov_b32_e32 v51, v4
	v_mov_b32_e32 v52, v4
	v_mov_b32_e32 v53, v4
	v_mov_b32_e32 v54, v4
	v_mov_b32_e32 v55, v4
	v_mov_b32_e32 v56, v4
	v_mov_b32_e32 v57, v4
	v_mov_b32_e32 v58, v4
	v_mov_b32_e32 v59, v4
	v_mov_b32_e32 v60, v4
	v_mov_b32_e32 v61, v4
	v_mov_b32_e32 v62, v4
	v_mov_b32_e32 v63, v4
	v_mov_b32_e32 v64, v4
	v_mov_b32_e32 v65, v4
	v_mov_b32_e32 v66, v4
	v_mov_b32_e32 v67, v4
	v_readlane_b32 s22, v127, 2
	v_readlane_b32 s23, v127, 3
	v_readfirstlane_b32 s98, v76
	s_movk_i32 s99, 0x6000
	s_add_i32 s101, s98, s99
	s_mov_b32 m0, s101
	s_add_i32 s101, s101, 0x2000
	global_load_lds_dwordx4 v[0:1], off
	s_mov_b32 m0, s101
	s_add_i32 s101, s101, 0x2000
	global_load_lds_dwordx4 v[68:69], off
	s_mov_b32 m0, s101
	s_add_i32 s99, s99, 0x6000
	global_load_lds_dwordx4 v[70:71], off
	s_cmp_eq_u32 s99, 0x12000
	s_cselect_b32 s99, 0, s99
	v_lshl_add_u64 v[0:1], v[0:1], 0, 64
	v_lshl_add_u64 v[68:69], v[68:69], 0, 64
	v_lshl_add_u64 v[70:71], v[70:71], 0, 64
	s_add_i32 s101, s98, s99
	s_mov_b32 m0, s101
	s_add_i32 s101, s101, 0x2000
	global_load_lds_dwordx4 v[0:1], off
	s_mov_b32 m0, s101
	s_add_i32 s101, s101, 0x2000
	global_load_lds_dwordx4 v[68:69], off
	s_mov_b32 m0, s101
	s_add_i32 s99, s99, 0x6000
	global_load_lds_dwordx4 v[70:71], off
	s_cmp_eq_u32 s99, 0x12000
	s_cselect_b32 s99, 0, s99
	v_lshl_add_u64 v[0:1], v[0:1], 0, 64
	v_lshl_add_u64 v[68:69], v[68:69], 0, 64
	v_lshl_add_u64 v[70:71], v[70:71], 0, 64
	s_mov_b32 s100, 0
	s_waitcnt vmcnt(6)
	s_barrier
	v_or_b32_e32 v112, s100, v77
	v_add_u32_e32 v113, v112, v78
	v_add_u32_e32 v112, v112, v79
	ds_read_b128 v[80:83], v113 offset:16384
	ds_read_b128 v[84:87], v113 offset:17408
	ds_read_b128 v[88:91], v113 offset:18432
	ds_read_b128 v[92:95], v113 offset:19456
	ds_read_b128 v[96:99], v112
	ds_read_b128 v[100:103], v112 offset:1024
	ds_read_b128 v[104:107], v112 offset:2048
	ds_read_b128 v[108:111], v112 offset:3072
	s_add_i32 s100, s100, 0x6000
	s_cmp_eq_u32 s100, 0x12000
	s_cselect_b32 s100, 0, s100
	s_cmp_ge_u32 s33, 0x100
	s_cbranch_scc1 .Lpp_B_1

; template <int MODE, bool SWAP, int MT>
; DI void gemm_tile(const int wv_, const Params& p, const u16* __restrict__ A, const u16* __restrict__ Bt, int brow, int bcol, char* smem, const float* gnext) {
;     ...
;   for (int t = 0; t < 32; ++t) {
;     asm volatile("s_waitcnt vmcnt(0)" ::: "memory");
;     __syncthreads();
;     if (t + 1 < 32) stage(t + 1, (t + 1) & 1);
;     const char* sA = smem + (t & 1) * 24576; const char* sB = sA + 16384;
;     bf16x8 Af[MT], Bf[4];
; #pragma unroll
;     for (int n = 0; n < 4; ++n) Bf[n] = *(const bf16x8*)(sB + (wc * 64 + n * 16 + fr) * 64 + fq * 16);
;     constexpr int MH = MT >= 2 ? MT / 2 : 1;
; #pragma unroll
;     for (int m = 0; m < MH; ++m) Af[m] = *(const bf16x8*)(sA + (wr * (16 * MT) + m * 16 + fr) * 64 + fq * 16);
;     __builtin_amdgcn_sched_barrier(0);
; #pragma unroll
;     for (int m = MH; m < MT; ++m) Af[m] = *(const bf16x8*)(sA + (wr * (16 * MT) + m * 16 + fr) * 64 + fq * 16);
; #pragma unroll
;     for (int m = 0; m < MH; ++m)
; #pragma unroll
;       for (int n = 0; n < 4; ++n)
;         acc[m][n] = SWAP ? __builtin_amdgcn_mfma_f32_16x16x32_bf16(Bf[n], Af[m], acc[m][n], 0, 0, 0)
;                          : __builtin_amdgcn_mfma_f32_16x16x32_bf16(Af[m], Bf[n], acc[m][n], 0, 0, 0);
;     __builtin_amdgcn_sched_barrier(0);
; #pragma unroll
;     for (int m = MH; m < MT; ++m)
; #pragma unroll
;       for (int n = 0; n < 4; ++n)
;         acc[m][n] = SWAP ? __builtin_amdgcn_mfma_f32_16x16x32_bf16(Bf[n], Af[m], acc[m][n], 0, 0, 0)
;                          : __builtin_amdgcn_mfma_f32_16x16x32_bf16(Af[m], Bf[n], acc[m][n], 0, 0, 0);
;   }
;     ...
;         const float rs = rowscale(p.ss, R);
; #pragma unroll
;         for (int n = 0; n < 4; ++n) { acc[m][n][0] *= rs; acc[m][n][1] *= rs; acc[m][n][2] *= rs; acc[m][n][3] *= rs; }
;         if (MODE == 0 && bcol >= 512 && bcol < 1536) {
;           int b = R / P, pos = R - b * P;
;           u16* dstb = (bcol < 1024 ? p.kc : p.vc);
; #pragma unroll
;           for (int n = 0; n < 4; ++n) {
;             int cc = (bcol & 511) + wc * 64 + n * 16 + fq * 4;
;             uint2 o; o.x = pack2(acc[m][n][0], acc[m][n][1]); o.y = pack2(acc[m][n][2], acc[m][n][3]);
;             *(uint2*)(dstb + ((size_t)((b * 8 + (cc >> 6)) * P + pos)) * 64 + (cc & 63)) = o;
;           }
;         } else {
;           const int LD = MODE == 0 ? LD_AB : LD_CD;
.Lpp_last_1:
	v_mfma_f32_16x16x32_bf16 v[32:35], v[80:83], v[104:107], v[32:35]
	v_mfma_f32_16x16x32_bf16 v[28:31], v[84:87], v[104:107], v[28:31]
	v_mfma_f32_16x16x32_bf16 v[24:27], v[88:91], v[104:107], v[24:27]
	v_mfma_f32_16x16x32_bf16 v[20:23], v[92:95], v[104:107], v[20:23]
	v_mfma_f32_16x16x32_bf16 v[16:19], v[80:83], v[108:111], v[16:19]
	v_mfma_f32_16x16x32_bf16 v[12:15], v[84:87], v[108:111], v[12:15]
	v_mfma_f32_16x16x32_bf16 v[8:11], v[88:91], v[108:111], v[8:11]
	v_mfma_f32_16x16x32_bf16 v[4:7], v[92:95], v[108:111], v[4:7]
	s_mov_b32 s0, s1
	s_branch .Lpp_exit_1
.Lpp_B_1:
	s_add_i32 s1, s0, 1
	s_waitcnt lgkmcnt(0)
	s_cmp_gt_u32 s0, 29
	s_cbranch_scc1 .Lpp_lastB_1
	s_waitcnt vmcnt(3)
	s_barrier
	s_cmp_gt_u32 s0, 28
	s_cbranch_scc1 .Lpp_nodmaB_1
	s_add_i32 s101, s98, s99
	s_mov_b32 m0, s101
	s_add_i32 s101, s101, 0x2000
	global_load_lds_dwordx4 v[0:1], off
	s_mov_b32 m0, s101
	s_add_i32 s101, s101, 0x2000
	global_load_lds_dwordx4 v[68:69], off
	s_mov_b32 m0, s101
	s_add_i32 s99, s99, 0x6000
	global_load_lds_dwordx4 v[70:71], off
	s_cmp_eq_u32 s99, 0x12000
	s_cselect_b32 s99, 0, s99
	v_lshl_add_u64 v[0:1], v[0:1], 0, 64
	v_lshl_add_u64 v[68:69], v[68:69], 0, 64
	v_lshl_add_u64 v[70:71], v[70:71], 0, 64
.Lpp_nodmaB_1:
	v_mfma_f32_16x16x32_bf16 v[64:67], v[80:83], v[96:99], v[64:67]
	v_mfma_f32_16x16x32_bf16 v[60:63], v[84:87], v[96:99], v[60:63]
	v_mfma_f32_16x16x32_bf16 v[56:59], v[88:91], v[96:99], v[56:59]
	v_mfma_f32_16x16x32_bf16 v[52:55], v[92:95], v[96:99], v[52:55]
	v_mfma_f32_16x16x32_bf16 v[48:51], v[80:83], v[100:103], v[48:51]
	v_mfma_f32_16x16x32_bf16 v[40:43], v[84:87], v[100:103], v[40:43]
	v_mfma_f32_16x16x32_bf16 v[36:39], v[88:91], v[100:103], v[36:39]
	v_mfma_f32_16x16x32_bf16 v[44:47], v[92:95], v[100:103], v[44:47]
	v_mfma_f32_16x16x32_bf16 v[32:35], v[80:83], v[104:107], v[32:35]
	v_mfma_f32_16x16x32_bf16 v[28:31], v[84:87], v[104:107], v[28:31]
	v_mfma_f32_16x16x32_bf16 v[24:27], v[88:91], v[104:107], v[24:27]
	v_mfma_f32_16x16x32_bf16 v[20:23], v[92:95], v[104:107], v[20:23]
	v_mfma_f32_16x16x32_bf16 v[16:19], v[80:83], v[108:111], v[16:19]
	v_mfma_f32_16x16x32_bf16 v[12:15], v[84:87], v[108:111], v[12:15]
	v_mfma_f32_16x16x32_bf16 v[8:11], v[88:91], v[108:111], v[8:11]
	v_mfma_f32_16x16x32_bf16 v[4:7], v[92:95], v[108:111], v[4:7]
	v_or_b32_e32 v112, s100, v77
	v_add_u32_e32 v113, v112, v78
	v_add_u32_e32 v112, v112, v79
	ds_read_b128 v[80:83], v113 offset:16384
	ds_read_b128 v[84:87], v113 offset:17408
	ds_read_b128 v[88:91], v113 offset:18432
	ds_read_b128 v[92:95], v113 offset:19456
	ds_read_b128 v[96:99], v112
	ds_read_b128 v[100:103], v112 offset:1024
	ds_read_b128 v[104:107], v112 offset:2048
	ds_read_b128 v[108:111], v112 offset:3072
	s_add_i32 s100, s100, 0x6000
	s_cmp_eq_u32 s100, 0x12000
	s_cselect_b32 s100, 0, s100
	s_mov_b32 s0, s1
	s_branch .Lpp_B_1
.Lpp_lastB_1:
	v_mfma_f32_16x16x32_bf16 v[64:67], v[80:83], v[96:99], v[64:67]
	v_mfma_f32_16x16x32_bf16 v[60:63], v[84:87], v[96:99], v[60:63]
	v_mfma_f32_16x16x32_bf16 v[56:59], v[88:91], v[96:99], v[56:59]
	v_mfma_f32_16x16x32_bf16 v[52:55], v[92:95], v[96:99], v[52:55]
	v_mfma_f32_16x16x32_bf16 v[48:51], v[80:83], v[100:103], v[48:51]
	v_mfma_f32_16x16x32_bf16 v[40:43], v[84:87], v[100:103], v[40:43]
	v_mfma_f32_16x16x32_bf16 v[36:39], v[88:91], v[100:103], v[36:39]
	v_mfma_f32_16x16x32_bf16 v[44:47], v[92:95], v[100:103], v[44:47]
	v_mfma_f32_16x16x32_bf16 v[32:35], v[80:83], v[104:107], v[32:35]
	v_mfma_f32_16x16x32_bf16 v[28:31], v[84:87], v[104:107], v[28:31]
	v_mfma_f32_16x16x32_bf16 v[24:27], v[88:91], v[104:107], v[24:27]
	v_mfma_f32_16x16x32_bf16 v[20:23], v[92:95], v[104:107], v[20:23]
	v_mfma_f32_16x16x32_bf16 v[16:19], v[80:83], v[108:111], v[16:19]
	v_mfma_f32_16x16x32_bf16 v[12:15], v[84:87], v[108:111], v[12:15]
	v_mfma_f32_16x16x32_bf16 v[8:11], v[88:91], v[108:111], v[8:11]
	v_mfma_f32_16x16x32_bf16 v[4:7], v[92:95], v[108:111], v[4:7]
	s_mov_b32 s0, s1
.Lpp_exit_1:
	v_add_u32_e32 v0, v77, v79
	v_add_u32_e32 v1, v77, v78
	s_waitcnt vmcnt(0)
	s_waitcnt vmcnt(0)
	s_barrier
	ds_read_b128 v[68:71], v0 offset:25600
	ds_read_b128 v[80:83], v0 offset:24576
	ds_read_b128 v[76:79], v1 offset:44032
	ds_read_b128 v[84:87], v1 offset:43008
	ds_read_b128 v[88:91], v1 offset:41984
	ds_read_b128 v[92:95], v1 offset:40960
	s_waitcnt lgkmcnt(0)
	v_mfma_f32_16x16x32_bf16 v[64:67], v[92:95], v[80:83], v[64:67]
	v_mfma_f32_16x16x32_bf16 v[60:63], v[88:91], v[80:83], v[60:63]
	v_mfma_f32_16x16x32_bf16 v[56:59], v[84:87], v[80:83], v[56:59]
	v_mfma_f32_16x16x32_bf16 v[52:55], v[76:79], v[80:83], v[52:55]
	ds_read_b128 v[80:83], v0 offset:26624
	ds_read_b128 v[96:99], v0 offset:27648
	v_mfma_f32_16x16x32_bf16 v[48:51], v[92:95], v[68:71], v[48:51]
	v_mfma_f32_16x16x32_bf16 v[40:43], v[88:91], v[68:71], v[40:43]
	v_mfma_f32_16x16x32_bf16 v[36:39], v[84:87], v[68:71], v[36:39]
	v_mfma_f32_16x16x32_bf16 v[44:47], v[76:79], v[68:71], v[44:47]
	v_or_b32_e32 v0, s18, v74
	v_lshl_add_u32 v68, v73, 6, v0
	v_lshlrev_b32_e32 v0, 6, v72
	v_lshlrev_b32_e32 v1, 2, v75
	v_ashrrev_i32_e32 v69, 31, v68
	v_or3_b32 v70, v0, v1, s15
	v_lshlrev_b64 v[0:1], 6, v[68:69]
	v_lshl_add_u64 v[0:1], s[90:91], 0, v[0:1]
	s_waitcnt lgkmcnt(1)
	v_mfma_f32_16x16x32_bf16 v[32:35], v[92:95], v[80:83], v[32:35]
	s_waitcnt lgkmcnt(0)
	s_barrier
; DI unsigned pack2(float a, float b) { f32x2_t v = {a, b}; return __builtin_bit_cast(unsigned, __builtin_convertvector(v, bf16x2_t)); }
; DI float rowscale(const float* ss, int R) {
;   const float4* q = (const float4*)(ss + (size_t)R * 16);
;   float4 a = q[0], b = q[1], c = q[2], d = q[3];
;   float t = ((a.x + a.y) + (a.z + a.w)) + ((b.x + b.y) + (b.z + b.w)) + ((c.x + c.y) + (c.z + c.w)) + ((d.x + d.y) + (d.z + d.w));
;   return rsqrtf(t * (1.f / 1024.f) + 1e-6f);
; }
; template <int MODE, bool SWAP, int MT>
; DI void gemm_tile(const int wv_, const Params& p, const u16* __restrict__ A, const u16* __restrict__ Bt, int brow, int bcol, char* smem, const float* gnext) {
;     ...
;         const float rs = rowscale(p.ss, R);
; #pragma unroll
;         for (int n = 0; n < 4; ++n) { acc[m][n][0] *= rs; acc[m][n][1] *= rs; acc[m][n][2] *= rs; acc[m][n][3] *= rs; }
;         if (MODE == 0 && bcol >= 512 && bcol < 1536) {
;           int b = R / P, pos = R - b * P;
;           u16* dstb = (bcol < 1024 ? p.kc : p.vc);
; #pragma unroll
;           for (int n = 0; n < 4; ++n) {
;             int cc = (bcol & 511) + wc * 64 + n * 16 + fq * 4;
;             uint2 o; o.x = pack2(acc[m][n][0], acc[m][n][1]); o.y = pack2(acc[m][n][2], acc[m][n][3]);
;             *(uint2*)(dstb + ((size_t)((b * 8 + (cc >> 6)) * P + pos)) * 64 + (cc & 63)) = o;
;           }
;         } else {
;           const int LD = MODE == 0 ? LD_AB : LD_CD;
;           u16* pr = p.proj + (size_t)R * LD;
; #pragma unroll
;           for (int n = 0; n < 4; ++n) {
;             int col = bcol + wc * 64 + n * 16 + fq * 4;
;             if (MODE == 1 || col < 4184) {
;               uint2 o; o.x = pack2(acc[m][n][0], acc[m][n][1]); o.y = pack2(acc[m][n][2], acc[m][n][3]);
;               int pcol = (MODE == 0 && col >= 1536) ? col - 1024 : col;
;               *(uint2*)(pr + pcol) = o;
	v_mfma_f32_16x16x32_bf16 v[28:31], v[88:91], v[80:83], v[28:31]
	v_mov_b32_e32 v69, 0x358637bd
	v_ashrrev_i32_e32 v71, 31, v70
	v_mfma_f32_16x16x32_bf16 v[24:27], v[84:87], v[80:83], v[24:27]
	v_mfma_f32_16x16x32_bf16 v[20:23], v[76:79], v[80:83], v[20:23]
	v_mfma_f32_16x16x32_bf16 v[8:11], v[84:87], v[96:99], v[8:11]
	v_mfma_f32_16x16x32_bf16 v[4:7], v[76:79], v[96:99], v[4:7]
	global_load_dwordx4 v[72:75], v[0:1], off offset:32
	global_load_dwordx4 v[76:79], v[0:1], off offset:16
	global_load_dwordx4 v[80:83], v[0:1], off
	global_load_dwordx4 v[84:87], v[0:1], off offset:48
	s_waitcnt vmcnt(3)
	v_mov_b32_e32 v2, v73
	v_mfma_f32_16x16x32_bf16 v[12:15], v[88:91], v[96:99], v[12:15]
	s_waitcnt vmcnt(1)
	v_mov_b32_e32 v0, v81
	v_mov_b32_e32 v1, v82
	v_mov_b32_e32 v88, v77
	v_mov_b32_e32 v89, v78
	v_mov_b32_e32 v81, v83
	v_mov_b32_e32 v77, v79
	v_pk_add_f32 v[0:1], v[0:1], v[80:81]
	v_pk_add_f32 v[76:77], v[88:89], v[76:77]
	v_pk_add_f32 v[72:73], v[72:73], v[2:3]
	v_mov_b32_e32 v2, v75
	v_pk_add_f32 v[0:1], v[0:1], v[0:1] op_sel:[0,1] op_sel_hi:[1,0]
	v_pk_add_f32 v[76:77], v[76:77], v[76:77] op_sel:[0,1] op_sel_hi:[1,0]
	v_pk_add_f32 v[74:75], v[74:75], v[2:3]
	s_waitcnt vmcnt(0)
	v_mov_b32_e32 v1, v84
	v_mov_b32_e32 v77, v85
	v_mov_b32_e32 v73, v86
	v_mov_b32_e32 v75, v87
	v_pk_add_f32 v[0:1], v[0:1], v[76:77]
	v_pk_add_f32 v[72:73], v[72:73], v[74:75]
	v_mfma_f32_16x16x32_bf16 v[16:19], v[92:95], v[96:99], v[16:19]
	v_add_f32_e64 v0, v0, v72
	v_add_f32_e64 v1, v1, v73
	v_add_f32_e32 v0, v0, v1
	v_fmamk_f32 v0, v0, 0x3a800000, v69
	v_cmp_gt_f32_e32 vcc, s96, v0
	v_mul_f32_e32 v1, 0x4b800000, v0
	s_nop 0
	v_cndmask_b32_e32 v0, v0, v1, vcc
	v_rsq_f32_e32 v0, v0
	s_nop 0
	v_mul_f32_e32 v1, 0x45800000, v0
	v_cndmask_b32_e32 v0, v0, v1, vcc
	v_pk_mul_f32 v[72:73], v[64:65], v[0:1] op_sel_hi:[1,0]
	v_pk_mul_f32 v[66:67], v[66:67], v[0:1] op_sel_hi:[1,0]
	v_pk_mul_f32 v[64:65], v[60:61], v[0:1] op_sel_hi:[1,0]
	v_pk_mul_f32 v[62:63], v[62:63], v[0:1] op_sel_hi:[1,0]
	v_pk_mul_f32 v[60:61], v[56:57], v[0:1] op_sel_hi:[1,0]
	v_pk_mul_f32 v[58:59], v[58:59], v[0:1] op_sel_hi:[1,0]
	v_pk_mul_f32 v[56:57], v[52:53], v[0:1] op_sel_hi:[1,0]
	v_pk_mul_f32 v[54:55], v[54:55], v[0:1] op_sel_hi:[1,0]
	v_mov_b64_e32 v[0:1], s[68:69]
	v_mad_i64_i32 v[74:75], s[0:1], v68, s34, v[0:1]
	v_lshlrev_b64 v[52:53], 1, v[70:71]
	v_cvt_pk_bf16_f32 v56, v56, v57
	v_cvt_pk_bf16_f32 v57, v54, v55
	v_or_b32_e32 v54, 16, v68
	v_cvt_pk_bf16_f32 v72, v72, v73
	v_cvt_pk_bf16_f32 v73, v66, v67
	v_lshl_add_u64 v[66:67], v[74:75], 0, v[52:53]
	v_ashrrev_i32_e32 v55, 31, v54
	v_cvt_pk_bf16_f32 v64, v64, v65
	v_cvt_pk_bf16_f32 v65, v62, v63
	v_cvt_pk_bf16_f32 v60, v60, v61
	v_cvt_pk_bf16_f32 v61, v58, v59
	global_store_dwordx2 v[66:67], v[56:57], off offset:96
	v_lshlrev_b64 v[56:57], 6, v[54:55]
	global_store_dwordx2 v[66:67], v[72:73], off
	global_store_dwordx2 v[66:67], v[64:65], off offset:32
	global_store_dwordx2 v[66:67], v[60:61], off offset:64
	v_lshl_add_u64 v[70:71], s[90:91], 0, v[56:57]
	global_load_dwordx4 v[56:59], v[70:71], off offset:32
	global_load_dwordx4 v[60:63], v[70:71], off offset:16
	global_load_dwordx4 v[64:67], v[70:71], off
	s_nop 0
	global_load_dwordx4 v[70:73], v[70:71], off offset:48
	s_waitcnt vmcnt(3)
	v_mov_b32_e32 v2, v57
	s_waitcnt vmcnt(2)
	v_mov_b32_e32 v76, v61
	s_waitcnt vmcnt(1)
	v_mov_b32_e32 v74, v65
	v_mov_b32_e32 v75, v66
	v_mov_b32_e32 v77, v62
	v_mov_b32_e32 v65, v67
	v_mov_b32_e32 v61, v63
	v_pk_add_f32 v[64:65], v[74:75], v[64:65]
	v_pk_add_f32 v[60:61], v[76:77], v[60:61]
	v_pk_add_f32 v[56:57], v[56:57], v[2:3]
	v_mov_b32_e32 v2, v59
	v_pk_add_f32 v[64:65], v[64:65], v[64:65] op_sel:[0,1] op_sel_hi:[1,0]
	v_pk_add_f32 v[60:61], v[60:61], v[60:61] op_sel:[0,1] op_sel_hi:[1,0]
	v_pk_add_f32 v[58:59], v[58:59], v[2:3]
	s_waitcnt vmcnt(0)
	v_mov_b32_e32 v65, v70
	v_mov_b32_e32 v61, v71
	v_mov_b32_e32 v57, v72
	v_mov_b32_e32 v59, v73
	v_pk_add_f32 v[60:61], v[64:65], v[60:61]
	v_pk_add_f32 v[56:57], v[56:57], v[58:59]
	s_nop 0
	v_pk_add_f32 v[56:57], v[60:61], v[56:57]
	s_nop 0
	v_add_f32_e32 v2, v56, v57
	v_fmamk_f32 v2, v2, 0x3a800000, v69
	v_cmp_gt_f32_e32 vcc, s96, v2
	v_mul_f32_e32 v55, 0x4b800000, v2
	s_nop 0
	v_cndmask_b32_e32 v2, v2, v55, vcc
	v_rsq_f32_e32 v2, v2
	s_nop 0
	v_mul_f32_e32 v55, 0x45800000, v2
	v_cndmask_b32_e32 v2, v2, v55, vcc
	v_pk_mul_f32 v[48:49], v[48:49], v[2:3] op_sel_hi:[1,0]
	v_pk_mul_f32 v[50:51], v[50:51], v[2:3] op_sel_hi:[1,0]
	v_pk_mul_f32 v[36:37], v[36:37], v[2:3] op_sel_hi:[1,0]
	v_pk_mul_f32 v[38:39], v[38:39], v[2:3] op_sel_hi:[1,0]
	v_mad_i64_i32 v[54:55], s[0:1], v54, s34, v[0:1]
	v_pk_mul_f32 v[44:45], v[44:45], v[2:3] op_sel_hi:[1,0]
	v_cvt_pk_bf16_f32 v48, v48, v49
	v_cvt_pk_bf16_f32 v49, v50, v51
	v_lshl_add_u64 v[50:51], v[54:55], 0, v[52:53]
	v_cvt_pk_bf16_f32 v36, v36, v37
	v_cvt_pk_bf16_f32 v37, v38, v39
	v_pk_mul_f32 v[46:47], v[46:47], v[2:3] op_sel_hi:[1,0]
	global_store_dwordx2 v[50:51], v[36:37], off offset:64
	v_cvt_pk_bf16_f32 v36, v44, v45
	v_or_b32_e32 v44, 32, v68
	v_pk_mul_f32 v[40:41], v[40:41], v[2:3] op_sel_hi:[1,0]
	v_pk_mul_f32 v[42:43], v[42:43], v[2:3] op_sel_hi:[1,0]
	v_cvt_pk_bf16_f32 v37, v46, v47
	v_ashrrev_i32_e32 v45, 31, v44
	v_cvt_pk_bf16_f32 v40, v40, v41
	v_cvt_pk_bf16_f32 v41, v42, v43
	global_store_dwordx2 v[50:51], v[36:37], off offset:96
	v_lshlrev_b64 v[36:37], 6, v[44:45]
	global_store_dwordx2 v[50:51], v[48:49], off
	global_store_dwordx2 v[50:51], v[40:41], off offset:32
	v_lshl_add_u64 v[50:51], s[90:91], 0, v[36:37]
	global_load_dwordx4 v[36:39], v[50:51], off offset:32
	global_load_dwordx4 v[40:43], v[50:51], off offset:16
	global_load_dwordx4 v[46:49], v[50:51], off
	global_load_dwordx4 v[54:57], v[50:51], off offset:48
	s_waitcnt vmcnt(3)
; DI unsigned pack2(float a, float b) { f32x2_t v = {a, b}; return __builtin_bit_cast(unsigned, __builtin_convertvector(v, bf16x2_t)); }
; DI float rowscale(const float* ss, int R) {
;   const float4* q = (const float4*)(ss + (size_t)R * 16);
;   float4 a = q[0], b = q[1], c = q[2], d = q[3];
;   float t = ((a.x + a.y) + (a.z + a.w)) + ((b.x + b.y) + (b.z + b.w)) + ((c.x + c.y) + (c.z + c.w)) + ((d.x + d.y) + (d.z + d.w));
;   return rsqrtf(t * (1.f / 1024.f) + 1e-6f);
; }
; template <int MODE, bool SWAP, int MT>
; DI void gemm_tile(const int wv_, const Params& p, const u16* __restrict__ A, const u16* __restrict__ Bt, int brow, int bcol, char* smem, const float* gnext) {
;     ...
;         const float rs = rowscale(p.ss, R);
; #pragma unroll
;         for (int n = 0; n < 4; ++n) { acc[m][n][0] *= rs; acc[m][n][1] *= rs; acc[m][n][2] *= rs; acc[m][n][3] *= rs; }
;         if (MODE == 0 && bcol >= 512 && bcol < 1536) {
;           int b = R / P, pos = R - b * P;
;           u16* dstb = (bcol < 1024 ? p.kc : p.vc);
; #pragma unroll
;           for (int n = 0; n < 4; ++n) {
;             int cc = (bcol & 511) + wc * 64 + n * 16 + fq * 4;
;             uint2 o; o.x = pack2(acc[m][n][0], acc[m][n][1]); o.y = pack2(acc[m][n][2], acc[m][n][3]);
;             *(uint2*)(dstb + ((size_t)((b * 8 + (cc >> 6)) * P + pos)) * 64 + (cc & 63)) = o;
;           }
;         } else {
;           const int LD = MODE == 0 ? LD_AB : LD_CD;
;           u16* pr = p.proj + (size_t)R * LD;
; #pragma unroll
;           for (int n = 0; n < 4; ++n) {
;             int col = bcol + wc * 64 + n * 16 + fq * 4;
;             if (MODE == 1 || col < 4184) {
;               uint2 o; o.x = pack2(acc[m][n][0], acc[m][n][1]); o.y = pack2(acc[m][n][2], acc[m][n][3]);
;               int pcol = (MODE == 0 && col >= 1536) ? col - 1024 : col;
;               *(uint2*)(pr + pcol) = o;
	v_mov_b32_e32 v2, v37
	s_waitcnt vmcnt(2)
	v_mov_b32_e32 v58, v41
	s_waitcnt vmcnt(1)
	v_mov_b32_e32 v50, v47
	v_mov_b32_e32 v51, v48
	v_mov_b32_e32 v59, v42
	v_mov_b32_e32 v47, v49
	v_mov_b32_e32 v41, v43
	v_pk_add_f32 v[46:47], v[50:51], v[46:47]
	v_pk_add_f32 v[40:41], v[58:59], v[40:41]
	v_pk_add_f32 v[36:37], v[36:37], v[2:3]
	v_mov_b32_e32 v2, v39
	v_pk_add_f32 v[46:47], v[46:47], v[46:47] op_sel:[0,1] op_sel_hi:[1,0]
	v_pk_add_f32 v[40:41], v[40:41], v[40:41] op_sel:[0,1] op_sel_hi:[1,0]
	v_pk_add_f32 v[38:39], v[38:39], v[2:3]
	s_waitcnt vmcnt(0)
	v_mov_b32_e32 v47, v54
	v_mov_b32_e32 v41, v55
	v_mov_b32_e32 v37, v56
	v_mov_b32_e32 v39, v57
	v_pk_add_f32 v[40:41], v[46:47], v[40:41]
	v_pk_add_f32 v[36:37], v[36:37], v[38:39]
	s_nop 0
	v_pk_add_f32 v[36:37], v[40:41], v[36:37]
	s_nop 0
	v_add_f32_e32 v2, v36, v37
	v_fmamk_f32 v2, v2, 0x3a800000, v69
	v_cmp_gt_f32_e32 vcc, s96, v2
	v_mul_f32_e32 v36, 0x4b800000, v2
	s_nop 0
	v_cndmask_b32_e32 v2, v2, v36, vcc
	v_rsq_f32_e32 v2, v2
	s_nop 0
	v_mul_f32_e32 v36, 0x45800000, v2
	v_cndmask_b32_e32 v2, v2, v36, vcc
	v_pk_mul_f32 v[32:33], v[32:33], v[2:3] op_sel_hi:[1,0]
	v_pk_mul_f32 v[34:35], v[34:35], v[2:3] op_sel_hi:[1,0]
	v_pk_mul_f32 v[28:29], v[28:29], v[2:3] op_sel_hi:[1,0]
	v_pk_mul_f32 v[30:31], v[30:31], v[2:3] op_sel_hi:[1,0]
	v_mad_i64_i32 v[36:37], s[0:1], v44, s34, v[0:1]
	v_cvt_pk_bf16_f32 v32, v32, v33
	v_cvt_pk_bf16_f32 v33, v34, v35
	v_lshl_add_u64 v[34:35], v[36:37], 0, v[52:53]
	v_cvt_pk_bf16_f32 v28, v28, v29
	v_cvt_pk_bf16_f32 v29, v30, v31
	v_pk_mul_f32 v[20:21], v[20:21], v[2:3] op_sel_hi:[1,0]
	v_pk_mul_f32 v[22:23], v[22:23], v[2:3] op_sel_hi:[1,0]
	global_store_dwordx2 v[34:35], v[28:29], off offset:32
	v_or_b32_e32 v28, 48, v68
	v_pk_mul_f32 v[24:25], v[24:25], v[2:3] op_sel_hi:[1,0]
	v_pk_mul_f32 v[26:27], v[26:27], v[2:3] op_sel_hi:[1,0]
	v_cvt_pk_bf16_f32 v20, v20, v21
	v_cvt_pk_bf16_f32 v21, v22, v23
	v_ashrrev_i32_e32 v29, 31, v28
	v_cvt_pk_bf16_f32 v24, v24, v25
	v_cvt_pk_bf16_f32 v25, v26, v27
	global_store_dwordx2 v[34:35], v[20:21], off offset:96
	v_lshlrev_b64 v[20:21], 6, v[28:29]
	global_store_dwordx2 v[34:35], v[32:33], off
	global_store_dwordx2 v[34:35], v[24:25], off offset:64
	v_lshl_add_u64 v[34:35], s[90:91], 0, v[20:21]
	global_load_dwordx4 v[20:23], v[34:35], off offset:32
	global_load_dwordx4 v[24:27], v[34:35], off offset:16
	global_load_dwordx4 v[30:33], v[34:35], off
	s_nop 0
	global_load_dwordx4 v[34:37], v[34:35], off offset:48
	v_mad_i64_i32 v[0:1], s[0:1], v28, s34, v[0:1]
	v_lshl_add_u64 v[0:1], v[0:1], 0, v[52:53]
	s_mov_b64 s[0:1], 0x60
	s_waitcnt vmcnt(3)
	v_mov_b32_e32 v2, v21
	s_waitcnt vmcnt(2)
	v_mov_b32_e32 v40, v25
	s_waitcnt vmcnt(1)
	v_mov_b32_e32 v38, v31
	v_mov_b32_e32 v39, v32
	v_mov_b32_e32 v41, v26
	v_mov_b32_e32 v31, v33
	v_mov_b32_e32 v25, v27
	v_pk_add_f32 v[30:31], v[38:39], v[30:31]
	v_pk_add_f32 v[24:25], v[40:41], v[24:25]
	v_pk_add_f32 v[20:21], v[20:21], v[2:3]
	v_mov_b32_e32 v2, v23
	v_pk_add_f32 v[30:31], v[30:31], v[30:31] op_sel:[0,1] op_sel_hi:[1,0]
	v_pk_add_f32 v[24:25], v[24:25], v[24:25] op_sel:[0,1] op_sel_hi:[1,0]
	v_pk_add_f32 v[22:23], v[22:23], v[2:3]
	s_waitcnt vmcnt(0)
	v_mov_b32_e32 v31, v34
	v_mov_b32_e32 v25, v35
	v_mov_b32_e32 v21, v36
	v_mov_b32_e32 v23, v37
	v_pk_add_f32 v[24:25], v[30:31], v[24:25]
	v_pk_add_f32 v[20:21], v[20:21], v[22:23]
	s_nop 0
	v_pk_add_f32 v[20:21], v[24:25], v[20:21]
	s_nop 0
	v_add_f32_e32 v2, v20, v21
	v_fmamk_f32 v2, v2, 0x3a800000, v69
	v_cmp_gt_f32_e32 vcc, s96, v2
	v_mul_f32_e32 v20, 0x4b800000, v2
	s_nop 0
	v_cndmask_b32_e32 v2, v2, v20, vcc
	v_rsq_f32_e32 v2, v2
	s_nop 0
	v_mul_f32_e32 v20, 0x45800000, v2
	v_cndmask_b32_e32 v2, v2, v20, vcc
	v_pk_mul_f32 v[16:17], v[16:17], v[2:3] op_sel_hi:[1,0]
	v_pk_mul_f32 v[18:19], v[18:19], v[2:3] op_sel_hi:[1,0]
	v_pk_mul_f32 v[12:13], v[12:13], v[2:3] op_sel_hi:[1,0]
	v_pk_mul_f32 v[14:15], v[14:15], v[2:3] op_sel_hi:[1,0]
	v_pk_mul_f32 v[20:21], v[4:5], v[2:3] op_sel_hi:[1,0]
	v_pk_mul_f32 v[4:5], v[6:7], v[2:3] op_sel_hi:[1,0]
	v_cvt_pk_bf16_f32 v6, v16, v17
	v_cvt_pk_bf16_f32 v7, v18, v19
	v_pk_mul_f32 v[8:9], v[8:9], v[2:3] op_sel_hi:[1,0]
	v_pk_mul_f32 v[10:11], v[10:11], v[2:3] op_sel_hi:[1,0]
	global_store_dwordx2 v[0:1], v[6:7], off
	v_cvt_pk_bf16_f32 v6, v12, v13
	v_cvt_pk_bf16_f32 v7, v14, v15
	global_store_dwordx2 v[0:1], v[6:7], off offset:32
	v_cvt_pk_bf16_f32 v6, v8, v9
	v_cvt_pk_bf16_f32 v7, v10, v11
	global_store_dwordx2 v[0:1], v[6:7], off offset:64
	v_cvt_pk_bf16_f32 v2, v20, v21
	v_lshl_add_u64 v[6:7], v[0:1], 0, s[0:1]
	s_mov_b64 s[0:1], 0
	global_store_dword v[0:1], v2, off offset:96
; template <int MODE, bool SWAP, int MT>
; DI void gemm_tile(const int wv_, const Params& p, const u16* __restrict__ A, const u16* __restrict__ Bt, int brow, int bcol, char* smem, const float* gnext) {
;     ...
;   const int tid = tid_, wid = tid >> 6, lane = tid & 63, wr = wid >> 1, wc = wid & 1, fr = lane & 15, fq = lane >> 4;
;   f32x4 acc[MT][4];
; #pragma unroll
;   for (int m = 0; m < MT; ++m)
; #pragma unroll
;     for (int n = 0; n < 4; ++n) acc[m][n] = f32x4{0.f, 0.f, 0.f, 0.f};
;   const int ra = tid >> 2, cb = (tid & 3) * 8;
;   const u16* ga0 = A + (size_t)(brow + ra) * 1024 + cb;
;   const u16* ga1 = A + (size_t)(brow + 128 + ra) * 1024 + cb;
;   const u16* gb0 = Bt + (size_t)(bcol + ra) * 1024 + cb;
;   auto stage = [&](int t, int buf) {
;     char* sA = smem + buf * 24576; char* sB = sA + 16384;
;     if (MT >= 2 || tid < 256) __builtin_amdgcn_global_load_lds((const unsigned*)(ga0 + t * 32), (unsigned*)(sA + tid * 16), 16, 0, 0);
;     if (MT == 4) __builtin_amdgcn_global_load_lds((const unsigned*)(ga1 + t * 32), (unsigned*)(sA + 8192 + tid * 16), 16, 0, 0);
;     __builtin_amdgcn_global_load_lds((const unsigned*)(gb0 + t * 32), (unsigned*)(sB + tid * 16), 16, 0, 0);
;   };
;   stage(0, 0);
;   for (int t = 0; t < 32; ++t) {
;     asm volatile("s_waitcnt vmcnt(0)" ::: "memory");
;     __syncthreads();
;     if (t + 1 < 32) stage(t + 1, (t + 1) & 1);
;     const char* sA = smem + (t & 1) * 24576; const char* sB = sA + 16384;
;     bf16x8 Af[MT], Bf[4];
; #pragma unroll
;     for (int n = 0; n < 4; ++n) Bf[n] = *(const bf16x8*)(sB + (wc * 64 + n * 16 + fr) * 64 + fq * 16);
;     constexpr int MH = MT >= 2 ? MT / 2 : 1;
; #pragma unroll
;     for (int m = 0; m < MH; ++m) Af[m] = *(const bf16x8*)(sA + (wr * (16 * MT) + m * 16 + fr) * 64 + fq * 16);
.LBB0_88:
	s_and_b64 vcc, exec, s[0:1]
	s_cbranch_vccz .LBB0_83
	s_mov_b32 s1, 0
	v_readlane_b32 s20, v127, 0
	v_mbcnt_lo_u32_b32 v0, -1, s1
	v_mbcnt_hi_u32_b32 v0, -1, v0
	v_add_u32_e32 v12, s33, v0
	s_mov_b32 s1, s16
	v_ashrrev_i32_e32 v13, 2, v12
	v_add_u32_e32 v0, s18, v13
	s_mov_b32 s1, s17
	v_ashrrev_i32_e32 v1, 31, v0
	v_lshlrev_b64 v[4:5], 11, v[0:1]
	v_readlane_b32 s21, v127, 1
	v_lshlrev_b32_e32 v76, 4, v12
	v_and_b32_e32 v2, 48, v76
	v_lshl_add_u64 v[6:7], s[20:21], 0, v[4:5]
	v_add_u32_e32 v0, 0x80, v0
	v_readfirstlane_b32 s1, v76
	v_lshl_add_u64 v[6:7], v[6:7], 0, v[2:3]
	v_ashrrev_i32_e32 v1, 31, v0
	s_mov_b32 m0, s1
	v_lshlrev_b64 v[8:9], 11, v[0:1]
	global_load_lds_dwordx4 v[6:7], off
	v_add_u32_e32 v6, 0x2000, v76
	v_lshl_add_u64 v[0:1], s[20:21], 0, v[8:9]
	v_add_u32_e32 v10, s15, v13
	v_readfirstlane_b32 s1, v6
	v_lshl_add_u64 v[0:1], v[0:1], 0, v[2:3]
	v_ashrrev_i32_e32 v11, 31, v10
	s_mov_b32 m0, s1
	v_lshlrev_b64 v[10:11], 11, v[10:11]
	global_load_lds_dwordx4 v[0:1], off
	v_add_u32_e32 v0, 0x4000, v76
	v_lshl_add_u64 v[10:11], s[2:3], 0, v[10:11]
	v_readfirstlane_b32 s1, v0
	v_lshl_add_u64 v[10:11], v[10:11], 0, v[2:3]
	s_mov_b32 m0, s1
	v_and_b32_e32 v73, 15, v12
	global_load_lds_dwordx4 v[10:11], off
	v_readlane_b32 s20, v127, 22
	v_bfe_u32 v72, v12, 6, 1
	v_ashrrev_i32_e32 v74, 7, v12
	v_lshlrev_b32_e32 v0, 6, v73
	v_or_b32_e32 v4, v4, v2
	v_readlane_b32 s21, v127, 23
	v_lshl_or_b32 v78, v72, 12, v0
	v_lshl_or_b32 v79, v74, 12, v0
	v_lshl_add_u64 v[0:1], s[20:21], 0, v[4:5]
	v_add_u32_e32 v4, s12, v13
	v_subrev_u32_e32 v4, s19, v4
	v_ashrrev_i32_e32 v5, 31, v4
	v_lshlrev_b64 v[4:5], 11, v[4:5]
	v_or_b32_e32 v4, v4, v2
	v_bfe_u32 v75, v12, 4, 2
	v_or_b32_e32 v8, v8, v2
	v_lshl_add_u64 v[70:71], s[4:5], 0, v[4:5]
	v_mov_b32_e32 v4, 0
	s_mov_b32 s0, 0
	v_lshlrev_b32_e32 v77, 4, v75
	v_lshl_add_u64 v[68:69], s[20:21], 0, v[8:9]
	v_mov_b32_e32 v5, v4
	v_mov_b32_e32 v6, v4
	v_mov_b32_e32 v7, v4
	v_mov_b32_e32 v8, v4
	v_mov_b32_e32 v9, v4
	v_mov_b32_e32 v10, v4
	v_mov_b32_e32 v11, v4
	v_mov_b32_e32 v12, v4
	v_mov_b32_e32 v13, v4
	v_mov_b32_e32 v14, v4
	v_mov_b32_e32 v15, v4
	v_mov_b32_e32 v16, v4
	v_mov_b32_e32 v17, v4
	v_mov_b32_e32 v18, v4
	v_mov_b32_e32 v19, v4
	v_mov_b32_e32 v20, v4
	v_mov_b32_e32 v21, v4
	v_mov_b32_e32 v22, v4
	v_mov_b32_e32 v23, v4
	v_mov_b32_e32 v24, v4
	v_mov_b32_e32 v25, v4
	v_mov_b32_e32 v26, v4
	v_mov_b32_e32 v27, v4
	v_mov_b32_e32 v28, v4
	v_mov_b32_e32 v29, v4
	v_mov_b32_e32 v30, v4
	v_mov_b32_e32 v31, v4
	v_mov_b32_e32 v32, v4
	v_mov_b32_e32 v33, v4
	v_mov_b32_e32 v34, v4
	v_mov_b32_e32 v35, v4
	v_mov_b32_e32 v36, v4
	v_mov_b32_e32 v37, v4
	v_mov_b32_e32 v38, v4
	v_mov_b32_e32 v39, v4
	v_mov_b32_e32 v40, v4
	v_mov_b32_e32 v41, v4
	v_mov_b32_e32 v42, v4
	v_mov_b32_e32 v43, v4
	v_mov_b32_e32 v44, v4
	v_mov_b32_e32 v45, v4
	v_mov_b32_e32 v46, v4
	v_mov_b32_e32 v47, v4
	v_mov_b32_e32 v48, v4
	v_mov_b32_e32 v49, v4
	v_mov_b32_e32 v50, v4
	v_mov_b32_e32 v51, v4
	v_mov_b32_e32 v52, v4
	v_mov_b32_e32 v53, v4
	v_mov_b32_e32 v54, v4
	v_mov_b32_e32 v55, v4
	v_mov_b32_e32 v56, v4
	v_mov_b32_e32 v57, v4
	v_mov_b32_e32 v58, v4
	v_mov_b32_e32 v59, v4
	v_mov_b32_e32 v60, v4
	v_mov_b32_e32 v61, v4
	v_mov_b32_e32 v62, v4
	v_mov_b32_e32 v63, v4
	v_mov_b32_e32 v64, v4
	v_mov_b32_e32 v65, v4
	v_mov_b32_e32 v66, v4
	v_mov_b32_e32 v67, v4
	v_readlane_b32 s22, v127, 2
	v_readlane_b32 s23, v127, 3
	v_readfirstlane_b32 s98, v76
	s_movk_i32 s99, 0x6000
	s_add_i32 s101, s98, s99
	s_mov_b32 m0, s101
	s_add_i32 s101, s101, 0x2000
	global_load_lds_dwordx4 v[0:1], off
	s_mov_b32 m0, s101
	s_add_i32 s101, s101, 0x2000
	global_load_lds_dwordx4 v[68:69], off
	s_mov_b32 m0, s101
	s_add_i32 s99, s99, 0x6000
	global_load_lds_dwordx4 v[70:71], off
	s_cmp_eq_u32 s99, 0x12000
	s_cselect_b32 s99, 0, s99
	v_lshl_add_u64 v[0:1], v[0:1], 0, 64
	v_lshl_add_u64 v[68:69], v[68:69], 0, 64
	v_lshl_add_u64 v[70:71], v[70:71], 0, 64
	s_add_i32 s101, s98, s99
	s_mov_b32 m0, s101
	s_add_i32 s101, s101, 0x2000
	global_load_lds_dwordx4 v[0:1], off
	s_mov_b32 m0, s101
	s_add_i32 s101, s101, 0x2000
	global_load_lds_dwordx4 v[68:69], off
	s_mov_b32 m0, s101
	s_add_i32 s99, s99, 0x6000
	global_load_lds_dwordx4 v[70:71], off
	s_cmp_eq_u32 s99, 0x12000
	s_cselect_b32 s99, 0, s99
	v_lshl_add_u64 v[0:1], v[0:1], 0, 64
	v_lshl_add_u64 v[68:69], v[68:69], 0, 64
	v_lshl_add_u64 v[70:71], v[70:71], 0, 64
	s_mov_b32 s100, 0
	s_waitcnt vmcnt(6)
	s_barrier
	v_or_b32_e32 v112, s100, v77
	v_add_u32_e32 v113, v112, v78
	v_add_u32_e32 v112, v112, v79
	ds_read_b128 v[80:83], v113 offset:16384
	ds_read_b128 v[84:87], v113 offset:17408
	ds_read_b128 v[88:91], v113 offset:18432
	ds_read_b128 v[92:95], v113 offset:19456
	ds_read_b128 v[96:99], v112
	ds_read_b128 v[100:103], v112 offset:1024
	ds_read_b128 v[104:107], v112 offset:2048
	ds_read_b128 v[108:111], v112 offset:3072
	s_add_i32 s100, s100, 0x6000
	s_cmp_eq_u32 s100, 0x12000
	s_cselect_b32 s100, 0, s100
	s_cmp_ge_u32 s33, 0x100
	s_cbranch_scc1 .Lpp_B_2

; template <int MODE, bool SWAP, int MT>
; DI void gemm_tile(const int wv_, const Params& p, const u16* __restrict__ A, const u16* __restrict__ Bt, int brow, int bcol, char* smem, const float* gnext) {
;     ...
;     for (int m = MH; m < MT; ++m)
; #pragma unroll
;       for (int n = 0; n < 4; ++n)
;         acc[m][n] = SWAP ? __builtin_amdgcn_mfma_f32_16x16x32_bf16(Bf[n], Af[m], acc[m][n], 0, 0, 0)
;                          : __builtin_amdgcn_mfma_f32_16x16x32_bf16(Af[m], Bf[n], acc[m][n], 0, 0, 0);
.Lpp_last_2:
	v_mfma_f32_16x16x32_bf16 v[32:35], v[104:107], v[80:83], v[32:35]
	v_mfma_f32_16x16x32_bf16 v[28:31], v[104:107], v[84:87], v[28:31]
	v_mfma_f32_16x16x32_bf16 v[24:27], v[104:107], v[88:91], v[24:27]
	v_mfma_f32_16x16x32_bf16 v[20:23], v[104:107], v[92:95], v[20:23]
	v_mfma_f32_16x16x32_bf16 v[16:19], v[108:111], v[80:83], v[16:19]
	v_mfma_f32_16x16x32_bf16 v[12:15], v[108:111], v[84:87], v[12:15]
	v_mfma_f32_16x16x32_bf16 v[8:11], v[108:111], v[88:91], v[8:11]
	v_mfma_f32_16x16x32_bf16 v[4:7], v[108:111], v[92:95], v[4:7]
	s_mov_b32 s0, s1
	s_branch .Lpp_exit_2

; DI unsigned pack2(float a, float b) { f32x2_t v = {a, b}; return __builtin_bit_cast(unsigned, __builtin_convertvector(v, bf16x2_t)); }
; template <int MODE, bool SWAP, int MT>
; DI void gemm_tile(const int wv_, const Params& p, const u16* __restrict__ A, const u16* __restrict__ Bt, int brow, int bcol, char* smem, const float* gnext) {
;     ...
;   for (int t = 0; t < 32; ++t) {
;     asm volatile("s_waitcnt vmcnt(0)" ::: "memory");
;     __syncthreads();
;     if (t + 1 < 32) stage(t + 1, (t + 1) & 1);
;     const char* sA = smem + (t & 1) * 24576; const char* sB = sA + 16384;
;     bf16x8 Af[MT], Bf[4];
; #pragma unroll
;     for (int n = 0; n < 4; ++n) Bf[n] = *(const bf16x8*)(sB + (wc * 64 + n * 16 + fr) * 64 + fq * 16);
;     constexpr int MH = MT >= 2 ? MT / 2 : 1;
; #pragma unroll
;     for (int m = 0; m < MH; ++m) Af[m] = *(const bf16x8*)(sA + (wr * (16 * MT) + m * 16 + fr) * 64 + fq * 16);
;     __builtin_amdgcn_sched_barrier(0);
; #pragma unroll
;     for (int m = MH; m < MT; ++m) Af[m] = *(const bf16x8*)(sA + (wr * (16 * MT) + m * 16 + fr) * 64 + fq * 16);
; #pragma unroll
;     for (int m = 0; m < MH; ++m)
; #pragma unroll
;       for (int n = 0; n < 4; ++n)
;         acc[m][n] = SWAP ? __builtin_amdgcn_mfma_f32_16x16x32_bf16(Bf[n], Af[m], acc[m][n], 0, 0, 0)
;                          : __builtin_amdgcn_mfma_f32_16x16x32_bf16(Af[m], Bf[n], acc[m][n], 0, 0, 0);
;     __builtin_amdgcn_sched_barrier(0);
; #pragma unroll
;     for (int m = MH; m < MT; ++m)
; #pragma unroll
;       for (int n = 0; n < 4; ++n)
;         acc[m][n] = SWAP ? __builtin_amdgcn_mfma_f32_16x16x32_bf16(Bf[n], Af[m], acc[m][n], 0, 0, 0)
;                          : __builtin_amdgcn_mfma_f32_16x16x32_bf16(Af[m], Bf[n], acc[m][n], 0, 0, 0);
;   }
;     ...
;     for (int m = 0; m < MT; ++m) {
;       int R = brow + wr * (16 * MT) + m * 16 + fq * 4;
;       int b = R / P, pos = R - b * P;
;       const float rs0 = rowscale(p.ss, R), rs1 = rowscale(p.ss, R + 1), rs2 = rowscale(p.ss, R + 2), rs3 = rowscale(p.ss, R + 3);
; #pragma unroll
;       for (int n = 0; n < 4; ++n) {
;         int col = bcol + wc * 64 + n * 16 + fr - 2560;
;         uint2 o; o.x = pack2(acc[m][n][0] * rs0, acc[m][n][1] * rs1); o.y = pack2(acc[m][n][2] * rs2, acc[m][n][3] * rs3);
;         *(uint2*)(p.vt + ((size_t)(b * 512 + col)) * P + pos) = o;
.Lpp_nodmaB_2:
	v_mfma_f32_16x16x32_bf16 v[64:67], v[96:99], v[80:83], v[64:67]
	v_mfma_f32_16x16x32_bf16 v[60:63], v[96:99], v[84:87], v[60:63]
	v_mfma_f32_16x16x32_bf16 v[56:59], v[96:99], v[88:91], v[56:59]
	v_mfma_f32_16x16x32_bf16 v[52:55], v[96:99], v[92:95], v[52:55]
	v_mfma_f32_16x16x32_bf16 v[48:51], v[100:103], v[80:83], v[48:51]
	v_mfma_f32_16x16x32_bf16 v[44:47], v[100:103], v[84:87], v[44:47]
	v_mfma_f32_16x16x32_bf16 v[40:43], v[100:103], v[88:91], v[40:43]
	v_mfma_f32_16x16x32_bf16 v[36:39], v[100:103], v[92:95], v[36:39]
	v_mfma_f32_16x16x32_bf16 v[32:35], v[104:107], v[80:83], v[32:35]
	v_mfma_f32_16x16x32_bf16 v[28:31], v[104:107], v[84:87], v[28:31]
	v_mfma_f32_16x16x32_bf16 v[24:27], v[104:107], v[88:91], v[24:27]
	v_mfma_f32_16x16x32_bf16 v[20:23], v[104:107], v[92:95], v[20:23]
	v_mfma_f32_16x16x32_bf16 v[16:19], v[108:111], v[80:83], v[16:19]
	v_mfma_f32_16x16x32_bf16 v[12:15], v[108:111], v[84:87], v[12:15]
	v_mfma_f32_16x16x32_bf16 v[8:11], v[108:111], v[88:91], v[8:11]
	v_mfma_f32_16x16x32_bf16 v[4:7], v[108:111], v[92:95], v[4:7]
	v_or_b32_e32 v112, s100, v77
	v_add_u32_e32 v113, v112, v78
	v_add_u32_e32 v112, v112, v79
	ds_read_b128 v[80:83], v113 offset:16384
	ds_read_b128 v[84:87], v113 offset:17408
	ds_read_b128 v[88:91], v113 offset:18432
	ds_read_b128 v[92:95], v113 offset:19456
	ds_read_b128 v[96:99], v112
	ds_read_b128 v[100:103], v112 offset:1024
	ds_read_b128 v[104:107], v112 offset:2048
	ds_read_b128 v[108:111], v112 offset:3072
	s_add_i32 s100, s100, 0x6000
	s_cmp_eq_u32 s100, 0x12000
	s_cselect_b32 s100, 0, s100
	s_mov_b32 s0, s1
	s_branch .Lpp_B_2
.Lpp_lastB_2:
	v_mfma_f32_16x16x32_bf16 v[64:67], v[96:99], v[80:83], v[64:67]
	v_mfma_f32_16x16x32_bf16 v[60:63], v[96:99], v[84:87], v[60:63]
	v_mfma_f32_16x16x32_bf16 v[56:59], v[96:99], v[88:91], v[56:59]
	v_mfma_f32_16x16x32_bf16 v[52:55], v[96:99], v[92:95], v[52:55]
	v_mfma_f32_16x16x32_bf16 v[48:51], v[100:103], v[80:83], v[48:51]
	v_mfma_f32_16x16x32_bf16 v[44:47], v[100:103], v[84:87], v[44:47]
	v_mfma_f32_16x16x32_bf16 v[40:43], v[100:103], v[88:91], v[40:43]
	v_mfma_f32_16x16x32_bf16 v[36:39], v[100:103], v[92:95], v[36:39]
	v_mfma_f32_16x16x32_bf16 v[32:35], v[104:107], v[80:83], v[32:35]
	v_mfma_f32_16x16x32_bf16 v[28:31], v[104:107], v[84:87], v[28:31]
	v_mfma_f32_16x16x32_bf16 v[24:27], v[104:107], v[88:91], v[24:27]
	v_mfma_f32_16x16x32_bf16 v[20:23], v[104:107], v[92:95], v[20:23]
	v_mfma_f32_16x16x32_bf16 v[16:19], v[108:111], v[80:83], v[16:19]
	v_mfma_f32_16x16x32_bf16 v[12:15], v[108:111], v[84:87], v[12:15]
	v_mfma_f32_16x16x32_bf16 v[8:11], v[108:111], v[88:91], v[8:11]
	v_mfma_f32_16x16x32_bf16 v[4:7], v[108:111], v[92:95], v[4:7]
	s_mov_b32 s0, s1
.Lpp_exit_2:
	v_add_u32_e32 v0, v77, v79
	v_add_u32_e32 v1, v77, v78
	s_waitcnt vmcnt(0)
	s_waitcnt vmcnt(0)
	s_barrier
	ds_read_b128 v[68:71], v0 offset:25600
	ds_read_b128 v[80:83], v0 offset:24576
	ds_read_b128 v[76:79], v1 offset:44032
	ds_read_b128 v[84:87], v1 offset:43008
	ds_read_b128 v[88:91], v1 offset:41984
	ds_read_b128 v[92:95], v1 offset:40960
	s_waitcnt lgkmcnt(0)
	v_mfma_f32_16x16x32_bf16 v[64:67], v[80:83], v[92:95], v[64:67]
	v_mfma_f32_16x16x32_bf16 v[60:63], v[80:83], v[88:91], v[60:63]
	v_mfma_f32_16x16x32_bf16 v[56:59], v[80:83], v[84:87], v[56:59]
	v_mfma_f32_16x16x32_bf16 v[52:55], v[80:83], v[76:79], v[52:55]
	ds_read_b128 v[80:83], v0 offset:26624
	ds_read_b128 v[96:99], v0 offset:27648
	v_mfma_f32_16x16x32_bf16 v[48:51], v[68:71], v[92:95], v[48:51]
	v_mfma_f32_16x16x32_bf16 v[44:47], v[68:71], v[88:91], v[44:47]
	v_mfma_f32_16x16x32_bf16 v[40:43], v[68:71], v[84:87], v[40:43]
	v_mfma_f32_16x16x32_bf16 v[36:39], v[68:71], v[76:79], v[36:39]
	v_lshl_add_u32 v0, v74, 6, s18
	s_waitcnt lgkmcnt(0)
	v_mfma_f32_16x16x32_bf16 v[16:19], v[96:99], v[92:95], v[16:19]
	s_addk_i32 s15, 0xf600
	s_movk_i32 s19, 0xdf80
	v_mfma_f32_16x16x32_bf16 v[12:15], v[96:99], v[88:91], v[12:15]
	s_barrier
	s_mov_b32 s0, 0x358637bd
	v_mfma_f32_16x16x32_bf16 v[8:11], v[96:99], v[84:87], v[8:11]
	s_mov_b32 s18, 0x3a800000
	s_mov_b32 s20, 0x45800000
	v_mfma_f32_16x16x32_bf16 v[4:7], v[96:99], v[76:79], v[4:7]
	v_lshl_or_b32 v96, v75, 2, v0
	v_lshlrev_b32_e32 v0, 6, v72
	v_or3_b32 v2, v0, s15, v73
	s_mov_b32 s15, 0x7e07e07f
	v_mul_hi_i32 v0, v96, s15
	v_lshrrev_b32_e32 v1, 31, v0
	v_ashrrev_i32_e32 v0, 12, v0
	v_ashrrev_i32_e32 v97, 31, v96
	v_or_b32_e32 v68, 2, v96
	v_add_u32_e32 v70, v0, v1
	v_lshlrev_b64 v[0:1], 6, v[96:97]
	v_ashrrev_i32_e32 v69, 31, v68
	v_lshl_add_u64 v[0:1], s[90:91], 0, v[0:1]
	v_lshlrev_b64 v[68:69], 6, v[68:69]
	v_mfma_f32_16x16x32_bf16 v[32:35], v[80:83], v[92:95], v[32:35]
	v_mad_i32_i24 v98, v70, s19, v96
	v_lshl_add_u64 v[102:103], s[90:91], 0, v[68:69]
	v_lshl_or_b32 v97, v70, 9, v2
	v_mfma_f32_16x16x32_bf16 v[28:31], v[80:83], v[88:91], v[28:31]
	v_ashrrev_i32_e32 v99, 31, v98
	v_mfma_f32_16x16x32_bf16 v[24:27], v[80:83], v[84:87], v[24:27]
	v_mfma_f32_16x16x32_bf16 v[20:23], v[80:83], v[76:79], v[20:23]
	global_load_dwordx4 v[68:71], v[0:1], off offset:112
	global_load_dwordx4 v[72:75], v[0:1], off offset:48
	global_load_dwordx4 v[76:79], v[0:1], off offset:96
	global_load_dwordx4 v[80:83], v[0:1], off offset:32
	global_load_dwordx4 v[84:87], v[0:1], off offset:80
	global_load_dwordx4 v[88:91], v[0:1], off offset:16
	global_load_dwordx4 v[92:95], v[0:1], off offset:64
	global_load_dwordx4 v[104:107], v[0:1], off
	s_waitcnt vmcnt(1)
	v_mov_b32_e32 v1, v92
	s_waitcnt vmcnt(0)
; DI unsigned pack2(float a, float b) { f32x2_t v = {a, b}; return __builtin_bit_cast(unsigned, __builtin_convertvector(v, bf16x2_t)); }
; DI float rowscale(const float* ss, int R) {
;   const float4* q = (const float4*)(ss + (size_t)R * 16);
;   float4 a = q[0], b = q[1], c = q[2], d = q[3];
;   float t = ((a.x + a.y) + (a.z + a.w)) + ((b.x + b.y) + (b.z + b.w)) + ((c.x + c.y) + (c.z + c.w)) + ((d.x + d.y) + (d.z + d.w));
;   return rsqrtf(t * (1.f / 1024.f) + 1e-6f);
; }
; template <int MODE, bool SWAP, int MT>
; DI void gemm_tile(const int wv_, const Params& p, const u16* __restrict__ A, const u16* __restrict__ Bt, int brow, int bcol, char* smem, const float* gnext) {
;     ...
;     for (int m = 0; m < MT; ++m) {
;       int R = brow + wr * (16 * MT) + m * 16 + fq * 4;
;       int b = R / P, pos = R - b * P;
;       const float rs0 = rowscale(p.ss, R), rs1 = rowscale(p.ss, R + 1), rs2 = rowscale(p.ss, R + 2), rs3 = rowscale(p.ss, R + 3);
; #pragma unroll
;       for (int n = 0; n < 4; ++n) {
;         int col = bcol + wc * 64 + n * 16 + fr - 2560;
;         uint2 o; o.x = pack2(acc[m][n][0] * rs0, acc[m][n][1] * rs1); o.y = pack2(acc[m][n][2] * rs2, acc[m][n][3] * rs3);
;         *(uint2*)(p.vt + ((size_t)(b * 512 + col)) * P + pos) = o;
;       }
	v_mov_b32_e32 v0, v104
	v_mov_b32_e32 v92, v105
	v_pk_add_f32 v[0:1], v[0:1], v[92:93]
	v_mov_b32_e32 v92, v106
	v_mov_b32_e32 v93, v94
	v_mov_b32_e32 v94, v107
	v_pk_add_f32 v[92:93], v[92:93], v[94:95]
	s_nop 0
	v_pk_add_f32 v[0:1], v[0:1], v[92:93]
	v_mov_b32_e32 v92, v88
	v_mov_b32_e32 v93, v84
	v_mov_b32_e32 v84, v89
	v_mov_b32_e32 v88, v90
	v_mov_b32_e32 v89, v86
	v_mov_b32_e32 v86, v91
	v_pk_add_f32 v[84:85], v[92:93], v[84:85]
	v_pk_add_f32 v[86:87], v[88:89], v[86:87]
	s_nop 0
	v_pk_add_f32 v[84:85], v[84:85], v[86:87]
	s_nop 0
	v_pk_add_f32 v[0:1], v[0:1], v[84:85]
	v_mov_b32_e32 v84, v80
	v_mov_b32_e32 v85, v76
	v_mov_b32_e32 v76, v81
	v_mov_b32_e32 v80, v82
	v_mov_b32_e32 v81, v78
	v_mov_b32_e32 v78, v83
	v_pk_add_f32 v[76:77], v[84:85], v[76:77]
	v_pk_add_f32 v[78:79], v[80:81], v[78:79]
	s_nop 0
	v_pk_add_f32 v[76:77], v[76:77], v[78:79]
	s_nop 0
	v_pk_add_f32 v[0:1], v[0:1], v[76:77]
	v_mov_b32_e32 v76, v72
	v_mov_b32_e32 v77, v68
	v_mov_b32_e32 v68, v73
	v_mov_b32_e32 v72, v74
	v_mov_b32_e32 v73, v70
	v_mov_b32_e32 v70, v75
	v_pk_add_f32 v[68:69], v[76:77], v[68:69]
	v_pk_add_f32 v[70:71], v[72:73], v[70:71]
	s_nop 0
	v_pk_add_f32 v[68:69], v[68:69], v[70:71]
	s_nop 0
	v_pk_add_f32 v[68:69], v[0:1], v[68:69]
	v_mov_b64_e32 v[0:1], s[0:1]
	v_pk_fma_f32 v[68:69], v[68:69], s[18:19], v[0:1] op_sel_hi:[1,0,0]
	s_nop 0
	v_mul_f32_e32 v70, 0x4b800000, v68
	v_cmp_gt_f32_e64 s[0:1], s96, v68
	v_cmp_gt_f32_e32 vcc, s96, v69
	s_nop 0
	v_cndmask_b32_e64 v68, v68, v70, s[0:1]
	v_mul_f32_e32 v70, 0x4b800000, v69
	v_cndmask_b32_e32 v69, v69, v70, vcc
	v_rsq_f32_e32 v68, v68
	v_rsq_f32_e32 v69, v69
	s_nop 0
	v_pk_mul_f32 v[70:71], v[68:69], s[20:21] op_sel_hi:[1,0]
	s_nop 0
	v_cndmask_b32_e32 v101, v69, v71, vcc
	v_cndmask_b32_e64 v100, v68, v70, s[0:1]
	global_load_dwordx4 v[68:71], v[102:103], off offset:112
	global_load_dwordx4 v[72:75], v[102:103], off offset:48
	global_load_dwordx4 v[76:79], v[102:103], off offset:96
	global_load_dwordx4 v[80:83], v[102:103], off offset:32
	global_load_dwordx4 v[84:87], v[102:103], off offset:80
	global_load_dwordx4 v[88:91], v[102:103], off offset:16
	global_load_dwordx4 v[92:95], v[102:103], off offset:64
	s_nop 0
	global_load_dwordx4 v[102:105], v[102:103], off
	v_pk_mul_f32 v[64:65], v[64:65], v[100:101]
	v_pk_mul_f32 v[52:53], v[52:53], v[100:101]
	v_cvt_pk_bf16_f32 v64, v64, v65
	v_cvt_pk_bf16_f32 v52, v52, v53
	v_pk_mul_f32 v[60:61], v[60:61], v[100:101]
	v_pk_mul_f32 v[56:57], v[56:57], v[100:101]
	v_cvt_pk_bf16_f32 v60, v60, v61
	v_cvt_pk_bf16_f32 v56, v56, v57
	s_waitcnt vmcnt(1)
	v_mov_b32_e32 v107, v92
	s_waitcnt vmcnt(0)
	v_mov_b32_e32 v106, v102
	v_mov_b32_e32 v92, v103
	v_mov_b32_e32 v102, v104
	v_mov_b32_e32 v103, v94
	v_mov_b32_e32 v94, v105
	v_pk_add_f32 v[92:93], v[106:107], v[92:93]
	v_pk_add_f32 v[94:95], v[102:103], v[94:95]
	s_nop 0
	v_pk_add_f32 v[92:93], v[92:93], v[94:95]
	v_mov_b32_e32 v94, v88
	v_mov_b32_e32 v95, v84
	v_mov_b32_e32 v84, v89
	v_mov_b32_e32 v88, v90
	v_mov_b32_e32 v89, v86
	v_mov_b32_e32 v86, v91
	v_pk_add_f32 v[84:85], v[94:95], v[84:85]
	v_pk_add_f32 v[86:87], v[88:89], v[86:87]
	s_nop 0
	v_pk_add_f32 v[84:85], v[84:85], v[86:87]
	v_mov_b32_e32 v86, v80
	v_mov_b32_e32 v87, v76
	v_mov_b32_e32 v76, v81
	v_mov_b32_e32 v80, v82
	v_mov_b32_e32 v81, v78
	v_mov_b32_e32 v78, v83
	v_pk_add_f32 v[76:77], v[86:87], v[76:77]
	v_pk_add_f32 v[78:79], v[80:81], v[78:79]
	v_pk_add_f32 v[84:85], v[92:93], v[84:85]
	v_pk_add_f32 v[76:77], v[76:77], v[78:79]
	v_mov_b32_e32 v78, v72
	v_mov_b32_e32 v79, v68
	v_mov_b32_e32 v68, v73
	v_mov_b32_e32 v72, v74
	v_mov_b32_e32 v73, v70
	v_mov_b32_e32 v70, v75
	v_pk_add_f32 v[68:69], v[78:79], v[68:69]
	v_pk_add_f32 v[70:71], v[72:73], v[70:71]
	v_pk_add_f32 v[76:77], v[84:85], v[76:77]
	v_pk_add_f32 v[68:69], v[68:69], v[70:71]
	v_mov_b64_e32 v[84:85], s[72:73]
	v_pk_add_f32 v[68:69], v[76:77], v[68:69]
	s_nop 0
	v_pk_fma_f32 v[68:69], v[68:69], s[18:19], v[0:1] op_sel_hi:[1,0,0]
	s_nop 0
	v_mul_f32_e32 v65, 0x4b800000, v68
	v_cmp_gt_f32_e64 s[0:1], s96, v68
	v_cmp_gt_f32_e32 vcc, s96, v69
	s_nop 0
	v_cndmask_b32_e64 v65, v68, v65, s[0:1]
	v_rsq_f32_e32 v68, v65
	v_mul_f32_e32 v65, 0x4b800000, v69
	v_cndmask_b32_e32 v65, v69, v65, vcc
	v_rsq_f32_e32 v69, v65
	s_nop 0
	v_pk_mul_f32 v[70:71], v[68:69], s[20:21] op_sel_hi:[1,0]
	s_nop 0
	v_cndmask_b32_e32 v69, v69, v71, vcc
	v_cndmask_b32_e64 v68, v68, v70, s[0:1]
	v_pk_mul_f32 v[54:55], v[54:55], v[68:69]
	s_movk_i32 s21, 0x4100
	v_cvt_pk_bf16_f32 v53, v54, v55
	v_or_b32_e32 v54, 48, v97
	v_lshlrev_b64 v[70:71], 1, v[98:99]
	v_mad_i64_i32 v[54:55], s[0:1], v54, s21, v[84:85]
	v_lshl_add_u64 v[54:55], v[54:55], 0, v[70:71]
	global_store_dwordx2 v[54:55], v[52:53], off
	v_or_b32_e32 v52, 16, v96
	v_mul_hi_i32 v53, v52, s15
	v_lshrrev_b32_e32 v54, 31, v53
	v_ashrrev_i32_e32 v53, 12, v53
	v_pk_mul_f32 v[62:63], v[62:63], v[68:69]
	v_pk_mul_f32 v[58:59], v[58:59], v[68:69]
	v_add_u32_e32 v54, v53, v54
	v_ashrrev_i32_e32 v53, 31, v52
	v_pk_mul_f32 v[66:67], v[66:67], v[68:69]
	v_cvt_pk_bf16_f32 v61, v62, v63
	v_or_b32_e32 v62, 16, v97
	v_cvt_pk_bf16_f32 v57, v58, v59
	v_or_b32_e32 v58, 32, v97
	v_mad_i32_i24 v86, v54, s19, v52
	v_lshlrev_b64 v[52:53], 6, v[52:53]
	v_cvt_pk_bf16_f32 v65, v66, v67
	v_mad_i64_i32 v[66:67], s[0:1], v97, s21, v[84:85]
	v_mad_i64_i32 v[62:63], s[0:1], v62, s21, v[84:85]
	v_mad_i64_i32 v[58:59], s[0:1], v58, s21, v[84:85]
	v_lshl_add_u64 v[82:83], s[90:91], 0, v[52:53]
	v_or_b32_e32 v52, 18, v96
	v_lshl_add_u64 v[66:67], v[66:67], 0, v[70:71]
	v_lshl_add_u64 v[62:63], v[62:63], 0, v[70:71]
	v_lshl_add_u64 v[58:59], v[58:59], 0, v[70:71]
	v_ashrrev_i32_e32 v53, 31, v52
	global_store_dwordx2 v[66:67], v[64:65], off
	global_store_dwordx2 v[62:63], v[60:61], off
	global_store_dwordx2 v[58:59], v[56:57], off
	v_lshlrev_b64 v[52:53], 6, v[52:53]
	v_lshl_add_u64 v[80:81], s[90:91], 0, v[52:53]
	v_lshl_or_b32 v90, v54, 9, v2
	global_load_dwordx4 v[52:55], v[82:83], off offset:112
	global_load_dwordx4 v[56:59], v[82:83], off offset:48
	global_load_dwordx4 v[60:63], v[82:83], off offset:96
	global_load_dwordx4 v[64:67], v[82:83], off offset:32
	global_load_dwordx4 v[68:71], v[82:83], off offset:80
	global_load_dwordx4 v[72:75], v[82:83], off offset:16
	global_load_dwordx4 v[76:79], v[82:83], off offset:64
	global_load_dwordx4 v[92:95], v[82:83], off
	v_ashrrev_i32_e32 v87, 31, v86
	s_waitcnt vmcnt(1)
; DI unsigned pack2(float a, float b) { f32x2_t v = {a, b}; return __builtin_bit_cast(unsigned, __builtin_convertvector(v, bf16x2_t)); }
; DI float rowscale(const float* ss, int R) {
;   const float4* q = (const float4*)(ss + (size_t)R * 16);
;   float4 a = q[0], b = q[1], c = q[2], d = q[3];
;   float t = ((a.x + a.y) + (a.z + a.w)) + ((b.x + b.y) + (b.z + b.w)) + ((c.x + c.y) + (c.z + c.w)) + ((d.x + d.y) + (d.z + d.w));
;   return rsqrtf(t * (1.f / 1024.f) + 1e-6f);
; }
; template <int MODE, bool SWAP, int MT>
; DI void gemm_tile(const int wv_, const Params& p, const u16* __restrict__ A, const u16* __restrict__ Bt, int brow, int bcol, char* smem, const float* gnext) {
;     ...
;     for (int m = 0; m < MT; ++m) {
;       int R = brow + wr * (16 * MT) + m * 16 + fq * 4;
;       int b = R / P, pos = R - b * P;
;       const float rs0 = rowscale(p.ss, R), rs1 = rowscale(p.ss, R + 1), rs2 = rowscale(p.ss, R + 2), rs3 = rowscale(p.ss, R + 3);
; #pragma unroll
;       for (int n = 0; n < 4; ++n) {
;         int col = bcol + wc * 64 + n * 16 + fr - 2560;
;         uint2 o; o.x = pack2(acc[m][n][0] * rs0, acc[m][n][1] * rs1); o.y = pack2(acc[m][n][2] * rs2, acc[m][n][3] * rs3);
;         *(uint2*)(p.vt + ((size_t)(b * 512 + col)) * P + pos) = o;
;       }
	v_mov_b32_e32 v83, v76
	s_waitcnt vmcnt(0)
	v_mov_b32_e32 v82, v92
	v_mov_b32_e32 v76, v93
	v_pk_add_f32 v[76:77], v[82:83], v[76:77]
	v_mov_b32_e32 v82, v94
	v_mov_b32_e32 v83, v78
	v_mov_b32_e32 v78, v95
	v_pk_add_f32 v[78:79], v[82:83], v[78:79]
	s_nop 0
	v_pk_add_f32 v[76:77], v[76:77], v[78:79]
	v_mov_b32_e32 v78, v72
	v_mov_b32_e32 v79, v68
	v_mov_b32_e32 v68, v73
	v_mov_b32_e32 v72, v74
	v_mov_b32_e32 v73, v70
	v_mov_b32_e32 v70, v75
	v_pk_add_f32 v[68:69], v[78:79], v[68:69]
	v_pk_add_f32 v[70:71], v[72:73], v[70:71]
	s_nop 0
	v_pk_add_f32 v[68:69], v[68:69], v[70:71]
	v_mov_b32_e32 v70, v64
	v_mov_b32_e32 v71, v60
	v_mov_b32_e32 v60, v65
	v_mov_b32_e32 v64, v66
	v_mov_b32_e32 v65, v62
	v_mov_b32_e32 v62, v67
	v_pk_add_f32 v[60:61], v[70:71], v[60:61]
	v_pk_add_f32 v[62:63], v[64:65], v[62:63]
	v_pk_add_f32 v[68:69], v[76:77], v[68:69]
	v_pk_add_f32 v[60:61], v[60:61], v[62:63]
	v_mov_b32_e32 v62, v56
	v_mov_b32_e32 v63, v52
	v_mov_b32_e32 v52, v57
	v_mov_b32_e32 v56, v58
	v_mov_b32_e32 v57, v54
	v_mov_b32_e32 v54, v59
	v_pk_add_f32 v[52:53], v[62:63], v[52:53]
	v_pk_add_f32 v[54:55], v[56:57], v[54:55]
	v_pk_add_f32 v[60:61], v[68:69], v[60:61]
	v_pk_add_f32 v[52:53], v[52:53], v[54:55]
	s_nop 0
	v_pk_add_f32 v[52:53], v[60:61], v[52:53]
	s_nop 0
	v_pk_fma_f32 v[52:53], v[52:53], s[18:19], v[0:1] op_sel_hi:[1,0,0]
	s_nop 0
	v_mul_f32_e32 v54, 0x4b800000, v52
	v_cmp_gt_f32_e64 s[0:1], s96, v52
	v_cmp_gt_f32_e32 vcc, s96, v53
	s_nop 0
	v_cndmask_b32_e64 v52, v52, v54, s[0:1]
	v_mul_f32_e32 v54, 0x4b800000, v53
	v_cndmask_b32_e32 v53, v53, v54, vcc
	v_rsq_f32_e32 v52, v52
	v_rsq_f32_e32 v53, v53
	s_nop 0
	v_pk_mul_f32 v[54:55], v[52:53], s[20:21] op_sel_hi:[1,0]
	s_nop 0
	v_cndmask_b32_e32 v89, v53, v55, vcc
	v_cndmask_b32_e64 v88, v52, v54, s[0:1]
	global_load_dwordx4 v[52:55], v[80:81], off offset:112
	global_load_dwordx4 v[56:59], v[80:81], off offset:48
	global_load_dwordx4 v[60:63], v[80:81], off offset:96
	global_load_dwordx4 v[64:67], v[80:81], off offset:32
	global_load_dwordx4 v[68:71], v[80:81], off offset:80
	global_load_dwordx4 v[72:75], v[80:81], off offset:16
	global_load_dwordx4 v[76:79], v[80:81], off offset:64
	s_nop 0
	global_load_dwordx4 v[80:83], v[80:81], off
	v_pk_mul_f32 v[48:49], v[48:49], v[88:89]
	v_pk_mul_f32 v[36:37], v[36:37], v[88:89]
	v_cvt_pk_bf16_f32 v48, v48, v49
	v_cvt_pk_bf16_f32 v36, v36, v37
	v_pk_mul_f32 v[44:45], v[44:45], v[88:89]
	v_pk_mul_f32 v[40:41], v[40:41], v[88:89]
	v_cvt_pk_bf16_f32 v44, v44, v45
	v_cvt_pk_bf16_f32 v40, v40, v41
	s_waitcnt vmcnt(1)
	v_mov_b32_e32 v93, v76
	s_waitcnt vmcnt(0)
	v_mov_b32_e32 v92, v80
	v_mov_b32_e32 v76, v81
	v_mov_b32_e32 v80, v82
	v_mov_b32_e32 v81, v78
	v_mov_b32_e32 v78, v83
	v_pk_add_f32 v[76:77], v[92:93], v[76:77]
	v_pk_add_f32 v[78:79], v[80:81], v[78:79]
	s_nop 0
	v_pk_add_f32 v[76:77], v[76:77], v[78:79]
	v_mov_b32_e32 v78, v72
	v_mov_b32_e32 v79, v68
	v_mov_b32_e32 v68, v73
	v_mov_b32_e32 v72, v74
	v_mov_b32_e32 v73, v70
	v_mov_b32_e32 v70, v75
	v_pk_add_f32 v[68:69], v[78:79], v[68:69]
	v_pk_add_f32 v[70:71], v[72:73], v[70:71]
	s_nop 0
	v_pk_add_f32 v[68:69], v[68:69], v[70:71]
	v_mov_b32_e32 v70, v64
	v_mov_b32_e32 v71, v60
	v_mov_b32_e32 v60, v65
	v_mov_b32_e32 v64, v66
	v_mov_b32_e32 v65, v62
	v_mov_b32_e32 v62, v67
	v_pk_add_f32 v[60:61], v[70:71], v[60:61]
	v_pk_add_f32 v[62:63], v[64:65], v[62:63]
	v_pk_add_f32 v[68:69], v[76:77], v[68:69]
	v_pk_add_f32 v[60:61], v[60:61], v[62:63]
	v_mov_b32_e32 v62, v56
	v_mov_b32_e32 v63, v52
	v_mov_b32_e32 v52, v57
	v_mov_b32_e32 v56, v58
	v_mov_b32_e32 v57, v54
	v_mov_b32_e32 v54, v59
	v_pk_add_f32 v[52:53], v[62:63], v[52:53]
	v_pk_add_f32 v[54:55], v[56:57], v[54:55]
	v_pk_add_f32 v[60:61], v[68:69], v[60:61]
	v_pk_add_f32 v[52:53], v[52:53], v[54:55]
	s_nop 0
	v_pk_add_f32 v[52:53], v[60:61], v[52:53]
	s_nop 0
	v_pk_fma_f32 v[52:53], v[52:53], s[18:19], v[0:1] op_sel_hi:[1,0,0]
	s_nop 0
	v_mul_f32_e32 v49, 0x4b800000, v52
	v_cmp_gt_f32_e64 s[0:1], s96, v52
	v_cmp_gt_f32_e32 vcc, s96, v53
	s_nop 0
	v_cndmask_b32_e64 v49, v52, v49, s[0:1]
	v_rsq_f32_e32 v52, v49
	v_mul_f32_e32 v49, 0x4b800000, v53
	v_cndmask_b32_e32 v49, v53, v49, vcc
	v_rsq_f32_e32 v53, v49
	s_nop 0
	v_pk_mul_f32 v[54:55], v[52:53], s[20:21] op_sel_hi:[1,0]
	s_nop 0
	v_cndmask_b32_e32 v53, v53, v55, vcc
	v_cndmask_b32_e64 v52, v52, v54, s[0:1]
	v_pk_mul_f32 v[38:39], v[38:39], v[52:53]
	v_lshlrev_b64 v[54:55], 1, v[86:87]
	v_cvt_pk_bf16_f32 v37, v38, v39
	v_or_b32_e32 v38, 48, v90
	v_mad_i64_i32 v[38:39], s[0:1], v38, s21, v[84:85]
	v_lshl_add_u64 v[38:39], v[38:39], 0, v[54:55]
	global_store_dwordx2 v[38:39], v[36:37], off
	v_or_b32_e32 v36, 32, v96
	v_mul_hi_i32 v37, v36, s15
	v_lshrrev_b32_e32 v38, 31, v37
	v_ashrrev_i32_e32 v37, 12, v37
	v_pk_mul_f32 v[46:47], v[46:47], v[52:53]
	v_pk_mul_f32 v[42:43], v[42:43], v[52:53]
	v_add_u32_e32 v38, v37, v38
	v_ashrrev_i32_e32 v37, 31, v36
	v_pk_mul_f32 v[50:51], v[50:51], v[52:53]
	v_cvt_pk_bf16_f32 v45, v46, v47
	v_or_b32_e32 v46, 16, v90
	v_cvt_pk_bf16_f32 v41, v42, v43
	v_or_b32_e32 v42, 32, v90
	v_mad_i32_i24 v68, v38, s19, v36
	v_lshlrev_b64 v[36:37], 6, v[36:37]
	v_cvt_pk_bf16_f32 v49, v50, v51
	v_mad_i64_i32 v[50:51], s[0:1], v90, s21, v[84:85]
	v_mad_i64_i32 v[46:47], s[0:1], v46, s21, v[84:85]
	v_mad_i64_i32 v[42:43], s[0:1], v42, s21, v[84:85]
	v_lshl_add_u64 v[66:67], s[90:91], 0, v[36:37]
	v_or_b32_e32 v36, 34, v96
	v_lshl_add_u64 v[50:51], v[50:51], 0, v[54:55]
	v_lshl_add_u64 v[46:47], v[46:47], 0, v[54:55]
	v_lshl_add_u64 v[42:43], v[42:43], 0, v[54:55]
	v_ashrrev_i32_e32 v37, 31, v36
	global_store_dwordx2 v[50:51], v[48:49], off
	global_store_dwordx2 v[46:47], v[44:45], off
	global_store_dwordx2 v[42:43], v[40:41], off
	v_lshlrev_b64 v[36:37], 6, v[36:37]
	v_lshl_add_u64 v[64:65], s[90:91], 0, v[36:37]
	v_lshl_or_b32 v72, v38, 9, v2
	global_load_dwordx4 v[36:39], v[66:67], off offset:112
	global_load_dwordx4 v[40:43], v[66:67], off offset:48
	global_load_dwordx4 v[44:47], v[66:67], off offset:96
	global_load_dwordx4 v[48:51], v[66:67], off offset:32
	global_load_dwordx4 v[52:55], v[66:67], off offset:80
	global_load_dwordx4 v[56:59], v[66:67], off offset:16
	global_load_dwordx4 v[60:63], v[66:67], off offset:64
	global_load_dwordx4 v[74:77], v[66:67], off
	v_ashrrev_i32_e32 v69, 31, v68
	s_waitcnt vmcnt(1)
; DI unsigned pack2(float a, float b) { f32x2_t v = {a, b}; return __builtin_bit_cast(unsigned, __builtin_convertvector(v, bf16x2_t)); }
; DI float rowscale(const float* ss, int R) {
;   const float4* q = (const float4*)(ss + (size_t)R * 16);
;   float4 a = q[0], b = q[1], c = q[2], d = q[3];
;   float t = ((a.x + a.y) + (a.z + a.w)) + ((b.x + b.y) + (b.z + b.w)) + ((c.x + c.y) + (c.z + c.w)) + ((d.x + d.y) + (d.z + d.w));
;   return rsqrtf(t * (1.f / 1024.f) + 1e-6f);
; }
; template <int MODE, bool SWAP, int MT>
; DI void gemm_tile(const int wv_, const Params& p, const u16* __restrict__ A, const u16* __restrict__ Bt, int brow, int bcol, char* smem, const float* gnext) {
;     ...
;     for (int m = 0; m < MT; ++m) {
;       int R = brow + wr * (16 * MT) + m * 16 + fq * 4;
;       int b = R / P, pos = R - b * P;
;       const float rs0 = rowscale(p.ss, R), rs1 = rowscale(p.ss, R + 1), rs2 = rowscale(p.ss, R + 2), rs3 = rowscale(p.ss, R + 3);
; #pragma unroll
;       for (int n = 0; n < 4; ++n) {
;         int col = bcol + wc * 64 + n * 16 + fr - 2560;
;         uint2 o; o.x = pack2(acc[m][n][0] * rs0, acc[m][n][1] * rs1); o.y = pack2(acc[m][n][2] * rs2, acc[m][n][3] * rs3);
;         *(uint2*)(p.vt + ((size_t)(b * 512 + col)) * P + pos) = o;
;       }
	v_mov_b32_e32 v67, v60
	s_waitcnt vmcnt(0)
	v_mov_b32_e32 v66, v74
	v_mov_b32_e32 v60, v75
	v_pk_add_f32 v[60:61], v[66:67], v[60:61]
	v_mov_b32_e32 v66, v76
	v_mov_b32_e32 v67, v62
	v_mov_b32_e32 v62, v77
	v_pk_add_f32 v[62:63], v[66:67], v[62:63]
	s_nop 0
	v_pk_add_f32 v[60:61], v[60:61], v[62:63]
	v_mov_b32_e32 v62, v56
	v_mov_b32_e32 v63, v52
	v_mov_b32_e32 v52, v57
	v_mov_b32_e32 v56, v58
	v_mov_b32_e32 v57, v54
	v_mov_b32_e32 v54, v59
	v_pk_add_f32 v[52:53], v[62:63], v[52:53]
	v_pk_add_f32 v[54:55], v[56:57], v[54:55]
	s_nop 0
	v_pk_add_f32 v[52:53], v[52:53], v[54:55]
	v_mov_b32_e32 v54, v48
	v_mov_b32_e32 v55, v44
	v_mov_b32_e32 v44, v49
	v_mov_b32_e32 v48, v50
	v_mov_b32_e32 v49, v46
	v_mov_b32_e32 v46, v51
	v_pk_add_f32 v[44:45], v[54:55], v[44:45]
	v_pk_add_f32 v[46:47], v[48:49], v[46:47]
	v_pk_add_f32 v[52:53], v[60:61], v[52:53]
	v_pk_add_f32 v[44:45], v[44:45], v[46:47]
	v_mov_b32_e32 v46, v40
	v_mov_b32_e32 v47, v36
	v_mov_b32_e32 v36, v41
	v_mov_b32_e32 v40, v42
	v_mov_b32_e32 v41, v38
	v_mov_b32_e32 v38, v43
	v_pk_add_f32 v[36:37], v[46:47], v[36:37]
	v_pk_add_f32 v[38:39], v[40:41], v[38:39]
	v_pk_add_f32 v[44:45], v[52:53], v[44:45]
	v_pk_add_f32 v[36:37], v[36:37], v[38:39]
	s_nop 0
	v_pk_add_f32 v[36:37], v[44:45], v[36:37]
	s_nop 0
	v_pk_fma_f32 v[36:37], v[36:37], s[18:19], v[0:1] op_sel_hi:[1,0,0]
	s_nop 0
	v_mul_f32_e32 v38, 0x4b800000, v36
	v_cmp_gt_f32_e64 s[0:1], s96, v36
	v_cmp_gt_f32_e32 vcc, s96, v37
	s_nop 0
	v_cndmask_b32_e64 v36, v36, v38, s[0:1]
	v_mul_f32_e32 v38, 0x4b800000, v37
	v_cndmask_b32_e32 v37, v37, v38, vcc
	v_rsq_f32_e32 v36, v36
	v_rsq_f32_e32 v37, v37
	s_nop 0
	v_pk_mul_f32 v[38:39], v[36:37], s[20:21] op_sel_hi:[1,0]
	s_nop 0
	v_cndmask_b32_e32 v71, v37, v39, vcc
	v_cndmask_b32_e64 v70, v36, v38, s[0:1]
	global_load_dwordx4 v[36:39], v[64:65], off offset:112
	global_load_dwordx4 v[40:43], v[64:65], off offset:48
	global_load_dwordx4 v[44:47], v[64:65], off offset:96
	global_load_dwordx4 v[48:51], v[64:65], off offset:32
	global_load_dwordx4 v[52:55], v[64:65], off offset:80
	global_load_dwordx4 v[56:59], v[64:65], off offset:16
	global_load_dwordx4 v[60:63], v[64:65], off offset:64
	s_nop 0
	global_load_dwordx4 v[64:67], v[64:65], off
	v_pk_mul_f32 v[32:33], v[32:33], v[70:71]
	v_pk_mul_f32 v[20:21], v[20:21], v[70:71]
	v_cvt_pk_bf16_f32 v32, v32, v33
	v_cvt_pk_bf16_f32 v20, v20, v21
	v_pk_mul_f32 v[28:29], v[28:29], v[70:71]
	v_pk_mul_f32 v[24:25], v[24:25], v[70:71]
	v_cvt_pk_bf16_f32 v28, v28, v29
	v_cvt_pk_bf16_f32 v24, v24, v25
	s_waitcnt vmcnt(1)
	v_mov_b32_e32 v75, v60
	s_waitcnt vmcnt(0)
	v_mov_b32_e32 v74, v64
	v_mov_b32_e32 v60, v65
	v_mov_b32_e32 v64, v66
	v_mov_b32_e32 v65, v62
	v_mov_b32_e32 v62, v67
	v_pk_add_f32 v[60:61], v[74:75], v[60:61]
	v_pk_add_f32 v[62:63], v[64:65], v[62:63]
	s_nop 0
	v_pk_add_f32 v[60:61], v[60:61], v[62:63]
	v_mov_b32_e32 v62, v56
	v_mov_b32_e32 v63, v52
	v_mov_b32_e32 v52, v57
	v_mov_b32_e32 v56, v58
	v_mov_b32_e32 v57, v54
	v_mov_b32_e32 v54, v59
	v_pk_add_f32 v[52:53], v[62:63], v[52:53]
	v_pk_add_f32 v[54:55], v[56:57], v[54:55]
	s_nop 0
	v_pk_add_f32 v[52:53], v[52:53], v[54:55]
	v_mov_b32_e32 v54, v48
	v_mov_b32_e32 v55, v44
	v_mov_b32_e32 v44, v49
	v_mov_b32_e32 v48, v50
	v_mov_b32_e32 v49, v46
	v_mov_b32_e32 v46, v51
	v_pk_add_f32 v[44:45], v[54:55], v[44:45]
	v_pk_add_f32 v[46:47], v[48:49], v[46:47]
	v_pk_add_f32 v[52:53], v[60:61], v[52:53]
	v_pk_add_f32 v[44:45], v[44:45], v[46:47]
	v_mov_b32_e32 v46, v40
	v_mov_b32_e32 v47, v36
	v_mov_b32_e32 v36, v41
	v_mov_b32_e32 v40, v42
	v_mov_b32_e32 v41, v38
	v_mov_b32_e32 v38, v43
	v_pk_add_f32 v[36:37], v[46:47], v[36:37]
	v_pk_add_f32 v[38:39], v[40:41], v[38:39]
	v_pk_add_f32 v[44:45], v[52:53], v[44:45]
	v_pk_add_f32 v[36:37], v[36:37], v[38:39]
	s_nop 0
	v_pk_add_f32 v[36:37], v[44:45], v[36:37]
	s_nop 0
	v_pk_fma_f32 v[36:37], v[36:37], s[18:19], v[0:1] op_sel_hi:[1,0,0]
	s_nop 0
	v_mul_f32_e32 v33, 0x4b800000, v36
	v_cmp_gt_f32_e64 s[0:1], s96, v36
	v_cmp_gt_f32_e32 vcc, s96, v37
	s_nop 0
	v_cndmask_b32_e64 v33, v36, v33, s[0:1]
	v_rsq_f32_e32 v36, v33
	v_mul_f32_e32 v33, 0x4b800000, v37
	v_cndmask_b32_e32 v33, v37, v33, vcc
	v_rsq_f32_e32 v37, v33
	s_nop 0
	v_pk_mul_f32 v[38:39], v[36:37], s[20:21] op_sel_hi:[1,0]
	s_nop 0
	v_cndmask_b32_e32 v37, v37, v39, vcc
	v_cndmask_b32_e64 v36, v36, v38, s[0:1]
	v_pk_mul_f32 v[22:23], v[22:23], v[36:37]
	v_lshlrev_b64 v[38:39], 1, v[68:69]
	v_cvt_pk_bf16_f32 v21, v22, v23
	v_or_b32_e32 v22, 48, v72
	v_mad_i64_i32 v[22:23], s[0:1], v22, s21, v[84:85]
	v_lshl_add_u64 v[22:23], v[22:23], 0, v[38:39]
	global_store_dwordx2 v[22:23], v[20:21], off
	v_or_b32_e32 v20, 48, v96
	v_mul_hi_i32 v21, v20, s15
	v_lshrrev_b32_e32 v22, 31, v21
	v_ashrrev_i32_e32 v21, 12, v21
	v_add_u32_e32 v40, v21, v22
	v_ashrrev_i32_e32 v21, 31, v20
	v_pk_mul_f32 v[30:31], v[30:31], v[36:37]
	v_pk_mul_f32 v[26:27], v[26:27], v[36:37]
	v_mad_i32_i24 v52, v40, s19, v20
	v_lshlrev_b64 v[20:21], 6, v[20:21]
	v_pk_mul_f32 v[34:35], v[34:35], v[36:37]
	v_cvt_pk_bf16_f32 v29, v30, v31
	v_or_b32_e32 v30, 16, v72
	v_cvt_pk_bf16_f32 v25, v26, v27
	v_or_b32_e32 v26, 32, v72
	v_lshl_add_u64 v[48:49], s[90:91], 0, v[20:21]
	v_or_b32_e32 v20, 50, v96
	v_cvt_pk_bf16_f32 v33, v34, v35
	v_mad_i64_i32 v[34:35], s[0:1], v72, s21, v[84:85]
	v_mad_i64_i32 v[30:31], s[0:1], v30, s21, v[84:85]
	v_mad_i64_i32 v[26:27], s[0:1], v26, s21, v[84:85]
	v_ashrrev_i32_e32 v21, 31, v20
	v_lshl_add_u64 v[34:35], v[34:35], 0, v[38:39]
	v_lshl_add_u64 v[30:31], v[30:31], 0, v[38:39]
	v_lshl_add_u64 v[26:27], v[26:27], 0, v[38:39]
	v_lshlrev_b64 v[20:21], 6, v[20:21]
	global_store_dwordx2 v[34:35], v[32:33], off
	global_store_dwordx2 v[30:31], v[28:29], off
	global_store_dwordx2 v[26:27], v[24:25], off
	v_lshl_add_u64 v[32:33], s[90:91], 0, v[20:21]
	global_load_dwordx4 v[20:23], v[32:33], off offset:48
	global_load_dwordx4 v[24:27], v[32:33], off offset:16
	global_load_dwordx4 v[28:31], v[32:33], off
	s_nop 0
	global_load_dwordx4 v[32:35], v[32:33], off offset:32
	v_lshl_or_b32 v2, v40, 9, v2
	v_ashrrev_i32_e32 v53, 31, v52
	s_waitcnt vmcnt(3)
; DI unsigned pack2(float a, float b) { f32x2_t v = {a, b}; return __builtin_bit_cast(unsigned, __builtin_convertvector(v, bf16x2_t)); }
; DI float rowscale(const float* ss, int R) {
;   const float4* q = (const float4*)(ss + (size_t)R * 16);
;   float4 a = q[0], b = q[1], c = q[2], d = q[3];
;   float t = ((a.x + a.y) + (a.z + a.w)) + ((b.x + b.y) + (b.z + b.w)) + ((c.x + c.y) + (c.z + c.w)) + ((d.x + d.y) + (d.z + d.w));
;   return rsqrtf(t * (1.f / 1024.f) + 1e-6f);
; }
; template <int MODE, bool SWAP, int MT>
; DI void gemm_tile(const int wv_, const Params& p, const u16* __restrict__ A, const u16* __restrict__ Bt, int brow, int bcol, char* smem, const float* gnext) {
;     ...
;     for (int m = 0; m < MT; ++m) {
;       int R = brow + wr * (16 * MT) + m * 16 + fq * 4;
;       int b = R / P, pos = R - b * P;
;       const float rs0 = rowscale(p.ss, R), rs1 = rowscale(p.ss, R + 1), rs2 = rowscale(p.ss, R + 2), rs3 = rowscale(p.ss, R + 3);
; #pragma unroll
;       for (int n = 0; n < 4; ++n) {
;         int col = bcol + wc * 64 + n * 16 + fr - 2560;
;         uint2 o; o.x = pack2(acc[m][n][0] * rs0, acc[m][n][1] * rs1); o.y = pack2(acc[m][n][2] * rs2, acc[m][n][3] * rs3);
;         *(uint2*)(p.vt + ((size_t)(b * 512 + col)) * P + pos) = o;
;       }
;     }
	v_mov_b32_e32 v37, v22
	v_mov_b32_e32 v36, v21
	s_waitcnt vmcnt(1)
	v_mov_b32_e32 v22, v29
	v_pk_add_f32 v[28:29], v[28:29], v[22:23]
	v_mov_b32_e32 v22, v31
	v_pk_add_f32 v[30:31], v[30:31], v[22:23]
	v_mov_b32_e32 v22, v25
	v_mov_b32_e32 v21, v23
	v_pk_add_f32 v[24:25], v[24:25], v[22:23]
	v_mov_b32_e32 v22, v27
	v_pk_add_f32 v[20:21], v[36:37], v[20:21]
	v_pk_add_f32 v[26:27], v[26:27], v[22:23]
	v_pk_add_f32 v[56:57], v[20:21], v[20:21] op_sel:[0,1] op_sel_hi:[1,0]
	v_or_b32_e32 v20, 51, v96
	s_waitcnt vmcnt(0)
	v_mov_b32_e32 v29, v32
	v_mov_b32_e32 v31, v33
	v_mov_b32_e32 v25, v34
	v_mov_b32_e32 v27, v35
	v_ashrrev_i32_e32 v21, 31, v20
	v_pk_add_f32 v[28:29], v[28:29], v[30:31]
	v_pk_add_f32 v[24:25], v[24:25], v[26:27]
	v_lshlrev_b64 v[20:21], 6, v[20:21]
	v_pk_add_f32 v[24:25], v[28:29], v[24:25]
	v_lshl_add_u64 v[32:33], s[90:91], 0, v[20:21]
	v_pk_add_f32 v[54:55], v[24:25], v[24:25] op_sel:[0,1] op_sel_hi:[1,0]
	global_load_dwordx4 v[20:23], v[32:33], off offset:32
	global_load_dwordx4 v[24:27], v[32:33], off offset:16
	global_load_dwordx4 v[28:31], v[32:33], off
	s_nop 0
	global_load_dwordx4 v[32:35], v[32:33], off offset:48
	s_waitcnt vmcnt(2)
	v_mov_b32_e32 v38, v25
	s_waitcnt vmcnt(1)
	v_mov_b32_e32 v36, v29
	v_mov_b32_e32 v37, v30
	v_mov_b32_e32 v39, v26
	v_mov_b32_e32 v29, v31
	v_mov_b32_e32 v25, v27
	v_mov_b32_e32 v26, v21
	v_pk_add_f32 v[28:29], v[36:37], v[28:29]
	v_pk_add_f32 v[24:25], v[38:39], v[24:25]
	v_pk_add_f32 v[20:21], v[20:21], v[26:27]
	v_mov_b32_e32 v26, v23
	v_pk_add_f32 v[28:29], v[28:29], v[28:29] op_sel:[0,1] op_sel_hi:[1,0]
	v_pk_add_f32 v[24:25], v[24:25], v[24:25] op_sel:[0,1] op_sel_hi:[1,0]
	v_pk_add_f32 v[22:23], v[22:23], v[26:27]
	s_waitcnt vmcnt(0)
	v_mov_b32_e32 v29, v32
	v_mov_b32_e32 v25, v33
	v_mov_b32_e32 v21, v34
	v_mov_b32_e32 v23, v35
	v_pk_add_f32 v[24:25], v[28:29], v[24:25]
	v_pk_add_f32 v[20:21], v[20:21], v[22:23]
	s_nop 0
	v_pk_add_f32 v[58:59], v[24:25], v[20:21]
	global_load_dwordx4 v[20:23], v[48:49], off offset:112
	global_load_dwordx4 v[24:27], v[48:49], off offset:48
	global_load_dwordx4 v[28:31], v[48:49], off offset:96
	global_load_dwordx4 v[32:35], v[48:49], off offset:32
	global_load_dwordx4 v[36:39], v[48:49], off offset:80
	global_load_dwordx4 v[40:43], v[48:49], off offset:16
	global_load_dwordx4 v[44:47], v[48:49], off offset:64
	s_nop 0
	global_load_dwordx4 v[48:51], v[48:49], off
	v_mov_b32_e32 v55, v58
	v_mov_b32_e32 v57, v59
	s_waitcnt vmcnt(1)
	v_mov_b32_e32 v61, v44
	s_waitcnt vmcnt(0)
	v_mov_b32_e32 v60, v48
	v_mov_b32_e32 v44, v49
	v_mov_b32_e32 v48, v50
	v_mov_b32_e32 v49, v46
	v_mov_b32_e32 v46, v51
	v_pk_add_f32 v[44:45], v[60:61], v[44:45]
	v_pk_add_f32 v[46:47], v[48:49], v[46:47]
	s_nop 0
	v_pk_add_f32 v[44:45], v[44:45], v[46:47]
	v_mov_b32_e32 v46, v40
	v_mov_b32_e32 v47, v36
	v_mov_b32_e32 v36, v41
	v_mov_b32_e32 v40, v42
	v_mov_b32_e32 v41, v38
	v_mov_b32_e32 v38, v43
	v_pk_add_f32 v[36:37], v[46:47], v[36:37]
	v_pk_add_f32 v[38:39], v[40:41], v[38:39]
	s_nop 0
	v_pk_add_f32 v[36:37], v[36:37], v[38:39]
	v_mov_b32_e32 v38, v32
	v_mov_b32_e32 v39, v28
	v_mov_b32_e32 v28, v33
	v_mov_b32_e32 v32, v34
	v_mov_b32_e32 v33, v30
	v_mov_b32_e32 v30, v35
	v_pk_add_f32 v[28:29], v[38:39], v[28:29]
	v_pk_add_f32 v[30:31], v[32:33], v[30:31]
	v_pk_add_f32 v[36:37], v[44:45], v[36:37]
	v_pk_add_f32 v[28:29], v[28:29], v[30:31]
	v_mov_b32_e32 v30, v24
	v_mov_b32_e32 v31, v20
	v_mov_b32_e32 v20, v25
	v_mov_b32_e32 v24, v26
	v_mov_b32_e32 v25, v22
	v_mov_b32_e32 v22, v27
	v_pk_add_f32 v[20:21], v[30:31], v[20:21]
	v_pk_add_f32 v[22:23], v[24:25], v[22:23]
	v_pk_add_f32 v[28:29], v[36:37], v[28:29]
	v_pk_add_f32 v[20:21], v[20:21], v[22:23]
	s_nop 0
	v_pk_add_f32 v[20:21], v[28:29], v[20:21]
	s_nop 0
	v_pk_fma_f32 v[20:21], v[20:21], s[18:19], v[0:1] op_sel_hi:[1,0,0]
	s_nop 0
	v_mul_f32_e32 v22, 0x4b800000, v20
	v_cmp_gt_f32_e64 s[0:1], s96, v20
	v_cmp_gt_f32_e32 vcc, s96, v21
	s_nop 0
	v_cndmask_b32_e64 v20, v20, v22, s[0:1]
	v_mul_f32_e32 v22, 0x4b800000, v21
	v_cndmask_b32_e32 v21, v21, v22, vcc
	v_rsq_f32_e32 v20, v20
	v_rsq_f32_e32 v21, v21
	s_nop 0
	v_pk_mul_f32 v[22:23], v[20:21], s[20:21] op_sel_hi:[1,0]
	s_nop 0
	v_cndmask_b32_e32 v21, v21, v23, vcc
	v_cndmask_b32_e64 v20, v20, v22, s[0:1]
	v_pk_add_f32 v[22:23], v[54:55], v[56:57]
	v_pk_mul_f32 v[16:17], v[16:17], v[20:21]
	v_pk_fma_f32 v[0:1], v[22:23], s[18:19], v[0:1] op_sel_hi:[1,0,0]
	v_cvt_pk_bf16_f32 v16, v16, v17
	v_mul_f32_e32 v17, 0x4b800000, v0
	v_cmp_gt_f32_e64 s[0:1], s96, v0
	v_cmp_gt_f32_e32 vcc, s96, v1
	v_pk_mul_f32 v[8:9], v[8:9], v[20:21]
	v_cndmask_b32_e64 v0, v0, v17, s[0:1]
	v_mul_f32_e32 v17, 0x4b800000, v1
	v_cndmask_b32_e32 v1, v1, v17, vcc
	v_rsq_f32_e32 v0, v0
	v_rsq_f32_e32 v1, v1
	v_cvt_pk_bf16_f32 v8, v8, v9
	v_pk_mul_f32 v[12:13], v[12:13], v[20:21]
	v_pk_mul_f32 v[4:5], v[4:5], v[20:21]
	v_pk_mul_f32 v[22:23], v[0:1], s[20:21] op_sel_hi:[1,0]
	v_cvt_pk_bf16_f32 v12, v12, v13
	v_cndmask_b32_e32 v1, v1, v23, vcc
	v_cndmask_b32_e64 v0, v0, v22, s[0:1]
	v_pk_mul_f32 v[10:11], v[10:11], v[0:1]
	v_lshlrev_b64 v[22:23], 1, v[52:53]
	v_cvt_pk_bf16_f32 v9, v10, v11
	v_or_b32_e32 v10, 32, v2
	v_mad_i64_i32 v[10:11], s[0:1], v10, s21, v[84:85]
	v_pk_mul_f32 v[14:15], v[14:15], v[0:1]
	v_lshl_add_u64 v[10:11], v[10:11], 0, v[22:23]
	v_pk_mul_f32 v[18:19], v[18:19], v[0:1]
	v_cvt_pk_bf16_f32 v13, v14, v15
	v_or_b32_e32 v14, 16, v2
	global_store_dwordx2 v[10:11], v[8:9], off
	v_cvt_pk_bf16_f32 v8, v4, v5
	v_pk_mul_f32 v[4:5], v[6:7], v[0:1]
	v_or_b32_e32 v0, 48, v2
	v_cvt_pk_bf16_f32 v17, v18, v19
	v_mad_i64_i32 v[18:19], s[0:1], v2, s21, v[84:85]
	v_mad_i64_i32 v[14:15], s[0:1], v14, s21, v[84:85]
	v_mad_i64_i32 v[0:1], s[0:1], v0, s21, v[84:85]
	v_lshl_add_u64 v[18:19], v[18:19], 0, v[22:23]
	v_lshl_add_u64 v[14:15], v[14:15], 0, v[22:23]
	v_lshl_add_u64 v[6:7], v[0:1], 0, v[22:23]
	global_store_dwordx2 v[18:19], v[16:17], off
	global_store_dwordx2 v[14:15], v[12:13], off
	global_store_dword v[6:7], v8, off
	s_branch .LBB0_83

; template <int MODE, bool SWAP, int MT>
; DI void gemm_tile(const int wv_, const Params& p, const u16* __restrict__ A, const u16* __restrict__ Bt, int brow, int bcol, char* smem, const float* gnext) {
;     ...
;   const int tid = tid_, wid = tid >> 6, lane = tid & 63, wr = wid >> 1, wc = wid & 1, fr = lane & 15, fq = lane >> 4;
;   f32x4 acc[MT][4];
; #pragma unroll
;   for (int m = 0; m < MT; ++m)
; #pragma unroll
;     for (int n = 0; n < 4; ++n) acc[m][n] = f32x4{0.f, 0.f, 0.f, 0.f};
;   const int ra = tid >> 2, cb = (tid & 3) * 8;
;   const u16* ga0 = A + (size_t)(brow + ra) * 1024 + cb;
;   const u16* ga1 = A + (size_t)(brow + 128 + ra) * 1024 + cb;
;   const u16* gb0 = Bt + (size_t)(bcol + ra) * 1024 + cb;
;   auto stage = [&](int t, int buf) {
;     char* sA = smem + buf * 24576; char* sB = sA + 16384;
;     if (MT >= 2 || tid < 256) __builtin_amdgcn_global_load_lds((const unsigned*)(ga0 + t * 32), (unsigned*)(sA + tid * 16), 16, 0, 0);
;     if (MT == 4) __builtin_amdgcn_global_load_lds((const unsigned*)(ga1 + t * 32), (unsigned*)(sA + 8192 + tid * 16), 16, 0, 0);
;     __builtin_amdgcn_global_load_lds((const unsigned*)(gb0 + t * 32), (unsigned*)(sB + tid * 16), 16, 0, 0);
;   };
;   stage(0, 0);
;   for (int t = 0; t < 32; ++t) {
;     asm volatile("s_waitcnt vmcnt(0)" ::: "memory");
;     __syncthreads();
;     if (t + 1 < 32) stage(t + 1, (t + 1) & 1);
;     const char* sA = smem + (t & 1) * 24576; const char* sB = sA + 16384;
;     bf16x8 Af[MT], Bf[4];
; #pragma unroll
;     for (int n = 0; n < 4; ++n) Bf[n] = *(const bf16x8*)(sB + (wc * 64 + n * 16 + fr) * 64 + fq * 16);
;     constexpr int MH = MT >= 2 ? MT / 2 : 1;
; #pragma unroll
;     for (int m = 0; m < MH; ++m) Af[m] = *(const bf16x8*)(sA + (wr * (16 * MT) + m * 16 + fr) * 64 + fq * 16);
; template <int MODE>
; DI void phase_gemm(const int wv_, const Params& p, const u16* A, const u16* Bt, int NT, char* smem, const float* gnext) {
;     ...
;     int tm = tile / NT, tn = tile - tm * NT;
;     if (MODE == 1 && tn >= 20 && tn < 24) gemm_tile<1, false, 4>(wv_, p, A, Bt, tm * 256, tn * 128, smem, gnext);
;     else gemm_tile<MODE, true, 4>(wv_, p, A, Bt, tm * 256, tn * 128, smem, gnext);
.LBB0_372:
	s_mul_hi_i32 s0, s22, 0x3e0f83e1
	s_mov_b32 s7, 0
	s_lshr_b32 s1, s0, 31
	s_ashr_i32 s0, s0, 3
	s_add_i32 s6, s0, s1
	v_mbcnt_lo_u32_b32 v0, -1, s7
	v_mbcnt_hi_u32_b32 v0, -1, v0
	s_mul_i32 s0, s6, 0xffffffdf
	v_add_u32_e32 v2, s33, v0
	s_add_i32 s1, s0, s22
	s_lshl_b32 s0, s6, 8
	s_mov_b32 s7, s16
	v_ashrrev_i32_e32 v12, 2, v2
	v_add_u32_e32 v0, s0, v12
	s_mov_b32 s7, s17
	v_ashrrev_i32_e32 v1, 31, v0
	v_readlane_b32 s8, v127, 0
	v_lshlrev_b64 v[4:5], 11, v[0:1]
	v_readlane_b32 s9, v127, 1
	v_lshlrev_b32_e32 v76, 4, v2
	v_bfe_u32 v72, v2, 6, 1
	v_ashrrev_i32_e32 v74, 7, v2
	v_and_b32_e32 v75, 15, v2
	v_bfe_u32 v73, v2, 4, 2
	v_lshl_add_u64 v[6:7], s[8:9], 0, v[4:5]
	v_and_b32_e32 v2, 48, v76
	v_add_u32_e32 v0, 0x80, v0
	v_readfirstlane_b32 s7, v76
	v_lshl_add_u64 v[6:7], v[6:7], 0, v[2:3]
	v_ashrrev_i32_e32 v1, 31, v0
	s_mov_b32 m0, s7
	s_lshl_b32 s23, s1, 7
	v_lshlrev_b64 v[8:9], 11, v[0:1]
	global_load_lds_dwordx4 v[6:7], off
	v_add_u32_e32 v6, 0x2000, v76
	v_lshl_add_u64 v[0:1], s[8:9], 0, v[8:9]
	v_add_u32_e32 v10, s23, v12
	v_readfirstlane_b32 s7, v6
	v_lshl_add_u64 v[0:1], v[0:1], 0, v[2:3]
	v_ashrrev_i32_e32 v11, 31, v10
	s_mov_b32 m0, s7
	v_lshlrev_b64 v[10:11], 11, v[10:11]
	global_load_lds_dwordx4 v[0:1], off
	v_add_u32_e32 v0, 0x4000, v76
	v_lshl_add_u64 v[10:11], s[2:3], 0, v[10:11]
	v_readfirstlane_b32 s7, v0
	v_lshl_add_u64 v[10:11], v[10:11], 0, v[2:3]
	s_mov_b32 m0, s7
	v_readlane_b32 s8, v127, 22
	global_load_lds_dwordx4 v[10:11], off
	v_lshlrev_b32_e32 v0, 6, v75
	v_or_b32_e32 v4, v4, v2
	v_readlane_b32 s9, v127, 23
	v_lshl_or_b32 v78, v72, 12, v0
	v_lshl_or_b32 v79, v74, 12, v0
	v_lshl_add_u64 v[0:1], s[8:9], 0, v[4:5]
	v_add_u32_e32 v4, s20, v12
	s_mulk_i32 s6, 0x1080
	v_subrev_u32_e32 v4, s6, v4
	v_ashrrev_i32_e32 v5, 31, v4
	v_lshlrev_b64 v[4:5], 11, v[4:5]
	v_or_b32_e32 v4, v4, v2
	v_or_b32_e32 v8, v8, v2
	v_lshl_add_u64 v[70:71], s[4:5], 0, v[4:5]
	v_mov_b32_e32 v4, 0
	s_mov_b32 s1, 0
	v_lshlrev_b32_e32 v77, 4, v73
	v_lshl_add_u64 v[68:69], s[8:9], 0, v[8:9]
	v_mov_b32_e32 v5, v4
	v_mov_b32_e32 v6, v4
	v_mov_b32_e32 v7, v4
	v_mov_b32_e32 v8, v4
	v_mov_b32_e32 v9, v4
	v_mov_b32_e32 v10, v4
	v_mov_b32_e32 v11, v4
	v_mov_b32_e32 v12, v4
	v_mov_b32_e32 v13, v4
	v_mov_b32_e32 v14, v4
	v_mov_b32_e32 v15, v4
	v_mov_b32_e32 v16, v4
	v_mov_b32_e32 v17, v4
	v_mov_b32_e32 v18, v4
	v_mov_b32_e32 v19, v4
	v_mov_b32_e32 v20, v4
	v_mov_b32_e32 v21, v4
	v_mov_b32_e32 v22, v4
	v_mov_b32_e32 v23, v4
	v_mov_b32_e32 v24, v4
	v_mov_b32_e32 v25, v4
	v_mov_b32_e32 v26, v4
	v_mov_b32_e32 v27, v4
	v_mov_b32_e32 v28, v4
	v_mov_b32_e32 v29, v4
	v_mov_b32_e32 v30, v4
	v_mov_b32_e32 v31, v4
	v_mov_b32_e32 v32, v4
	v_mov_b32_e32 v33, v4
	v_mov_b32_e32 v34, v4
	v_mov_b32_e32 v35, v4
	v_mov_b32_e32 v44, v4
	v_mov_b32_e32 v45, v4
	v_mov_b32_e32 v46, v4
	v_mov_b32_e32 v47, v4
	v_mov_b32_e32 v36, v4
	v_mov_b32_e32 v37, v4
	v_mov_b32_e32 v38, v4
	v_mov_b32_e32 v39, v4
	v_mov_b32_e32 v40, v4
	v_mov_b32_e32 v41, v4
	v_mov_b32_e32 v42, v4
	v_mov_b32_e32 v43, v4
	v_mov_b32_e32 v48, v4
	v_mov_b32_e32 v49, v4
	v_mov_b32_e32 v50, v4
	v_mov_b32_e32 v51, v4
	v_mov_b32_e32 v52, v4
	v_mov_b32_e32 v53, v4
	v_mov_b32_e32 v54, v4
	v_mov_b32_e32 v55, v4
	v_mov_b32_e32 v56, v4
	v_mov_b32_e32 v57, v4
	v_mov_b32_e32 v58, v4
	v_mov_b32_e32 v59, v4
	v_mov_b32_e32 v60, v4
	v_mov_b32_e32 v61, v4
	v_mov_b32_e32 v62, v4
	v_mov_b32_e32 v63, v4
	v_mov_b32_e32 v64, v4
	v_mov_b32_e32 v65, v4
	v_mov_b32_e32 v66, v4
	v_mov_b32_e32 v67, v4
	v_readlane_b32 s10, v127, 2
	v_readlane_b32 s11, v127, 3
	v_readfirstlane_b32 s98, v76
	s_movk_i32 s99, 0x6000
	s_add_i32 s101, s98, s99
	s_mov_b32 m0, s101
	s_add_i32 s101, s101, 0x2000
	global_load_lds_dwordx4 v[0:1], off
	s_mov_b32 m0, s101
	s_add_i32 s101, s101, 0x2000
	global_load_lds_dwordx4 v[68:69], off
	s_mov_b32 m0, s101
	s_add_i32 s99, s99, 0x6000
	global_load_lds_dwordx4 v[70:71], off
	s_cmp_eq_u32 s99, 0x12000
	s_cselect_b32 s99, 0, s99
	v_lshl_add_u64 v[0:1], v[0:1], 0, 64
	v_lshl_add_u64 v[68:69], v[68:69], 0, 64
	v_lshl_add_u64 v[70:71], v[70:71], 0, 64
	s_add_i32 s101, s98, s99
	s_mov_b32 m0, s101
	s_add_i32 s101, s101, 0x2000
	global_load_lds_dwordx4 v[0:1], off
	s_mov_b32 m0, s101
	s_add_i32 s101, s101, 0x2000
	global_load_lds_dwordx4 v[68:69], off
	s_mov_b32 m0, s101
	s_add_i32 s99, s99, 0x6000
	global_load_lds_dwordx4 v[70:71], off
	s_cmp_eq_u32 s99, 0x12000
	s_cselect_b32 s99, 0, s99
	v_lshl_add_u64 v[0:1], v[0:1], 0, 64
	v_lshl_add_u64 v[68:69], v[68:69], 0, 64
	v_lshl_add_u64 v[70:71], v[70:71], 0, 64
	s_mov_b32 s100, 0
	s_waitcnt vmcnt(6)
	s_barrier
	v_or_b32_e32 v112, s100, v77
	v_add_u32_e32 v113, v112, v78
	v_add_u32_e32 v112, v112, v79
	ds_read_b128 v[80:83], v113 offset:16384
	ds_read_b128 v[84:87], v113 offset:17408
	ds_read_b128 v[88:91], v113 offset:18432
	ds_read_b128 v[92:95], v113 offset:19456
	ds_read_b128 v[96:99], v112
	ds_read_b128 v[100:103], v112 offset:1024
	ds_read_b128 v[104:107], v112 offset:2048
	ds_read_b128 v[108:111], v112 offset:3072
	s_add_i32 s100, s100, 0x6000
	s_cmp_eq_u32 s100, 0x12000
	s_cselect_b32 s100, 0, s100
	s_cmp_ge_u32 s33, 0x100
	s_cbranch_scc1 .Lpp_B_3

; template <int MODE, bool SWAP, int MT>
; DI void gemm_tile(const int wv_, const Params& p, const u16* __restrict__ A, const u16* __restrict__ Bt, int brow, int bcol, char* smem, const float* gnext) {
;     ...
;   for (int t = 0; t < 32; ++t) {
;     asm volatile("s_waitcnt vmcnt(0)" ::: "memory");
;     __syncthreads();
;     if (t + 1 < 32) stage(t + 1, (t + 1) & 1);
;     const char* sA = smem + (t & 1) * 24576; const char* sB = sA + 16384;
;     bf16x8 Af[MT], Bf[4];
; #pragma unroll
;     for (int n = 0; n < 4; ++n) Bf[n] = *(const bf16x8*)(sB + (wc * 64 + n * 16 + fr) * 64 + fq * 16);
;     constexpr int MH = MT >= 2 ? MT / 2 : 1;
; #pragma unroll
;     for (int m = 0; m < MH; ++m) Af[m] = *(const bf16x8*)(sA + (wr * (16 * MT) + m * 16 + fr) * 64 + fq * 16);
;     __builtin_amdgcn_sched_barrier(0);
; #pragma unroll
;     for (int m = MH; m < MT; ++m) Af[m] = *(const bf16x8*)(sA + (wr * (16 * MT) + m * 16 + fr) * 64 + fq * 16);
; #pragma unroll
;     for (int m = 0; m < MH; ++m)
; #pragma unroll
;       for (int n = 0; n < 4; ++n)
;         acc[m][n] = SWAP ? __builtin_amdgcn_mfma_f32_16x16x32_bf16(Bf[n], Af[m], acc[m][n], 0, 0, 0)
;                          : __builtin_amdgcn_mfma_f32_16x16x32_bf16(Af[m], Bf[n], acc[m][n], 0, 0, 0);
;     __builtin_amdgcn_sched_barrier(0);
; #pragma unroll
;     for (int m = MH; m < MT; ++m)
; #pragma unroll
;       for (int n = 0; n < 4; ++n)
;         acc[m][n] = SWAP ? __builtin_amdgcn_mfma_f32_16x16x32_bf16(Bf[n], Af[m], acc[m][n], 0, 0, 0)
;                          : __builtin_amdgcn_mfma_f32_16x16x32_bf16(Af[m], Bf[n], acc[m][n], 0, 0, 0);
;   }
.Lpp_last_3:
	v_mfma_f32_16x16x32_bf16 v[32:35], v[80:83], v[104:107], v[32:35]
	v_mfma_f32_16x16x32_bf16 v[28:31], v[84:87], v[104:107], v[28:31]
	v_mfma_f32_16x16x32_bf16 v[24:27], v[88:91], v[104:107], v[24:27]
	v_mfma_f32_16x16x32_bf16 v[20:23], v[92:95], v[104:107], v[20:23]
	v_mfma_f32_16x16x32_bf16 v[16:19], v[80:83], v[108:111], v[16:19]
	v_mfma_f32_16x16x32_bf16 v[12:15], v[84:87], v[108:111], v[12:15]
	v_mfma_f32_16x16x32_bf16 v[8:11], v[88:91], v[108:111], v[8:11]
	v_mfma_f32_16x16x32_bf16 v[4:7], v[92:95], v[108:111], v[4:7]
	s_mov_b32 s1, s6
	s_branch .Lpp_exit_3
.Lpp_B_3:
	s_add_i32 s6, s1, 1
	s_waitcnt lgkmcnt(0)
	s_cmp_gt_u32 s1, 29
	s_cbranch_scc1 .Lpp_lastB_3
	s_waitcnt vmcnt(3)
	s_barrier
	s_cmp_gt_u32 s1, 28
	s_cbranch_scc1 .Lpp_nodmaB_3
	s_add_i32 s101, s98, s99
	s_mov_b32 m0, s101
	s_add_i32 s101, s101, 0x2000
	global_load_lds_dwordx4 v[0:1], off
	s_mov_b32 m0, s101
	s_add_i32 s101, s101, 0x2000
	global_load_lds_dwordx4 v[68:69], off
	s_mov_b32 m0, s101
	s_add_i32 s99, s99, 0x6000
	global_load_lds_dwordx4 v[70:71], off
	s_cmp_eq_u32 s99, 0x12000
	s_cselect_b32 s99, 0, s99
	v_lshl_add_u64 v[0:1], v[0:1], 0, 64
	v_lshl_add_u64 v[68:69], v[68:69], 0, 64
	v_lshl_add_u64 v[70:71], v[70:71], 0, 64
.Lpp_nodmaB_3:
	v_mfma_f32_16x16x32_bf16 v[64:67], v[80:83], v[96:99], v[64:67]
	v_mfma_f32_16x16x32_bf16 v[60:63], v[84:87], v[96:99], v[60:63]
	v_mfma_f32_16x16x32_bf16 v[56:59], v[88:91], v[96:99], v[56:59]
	v_mfma_f32_16x16x32_bf16 v[52:55], v[92:95], v[96:99], v[52:55]
	v_mfma_f32_16x16x32_bf16 v[48:51], v[80:83], v[100:103], v[48:51]
	v_mfma_f32_16x16x32_bf16 v[40:43], v[84:87], v[100:103], v[40:43]
	v_mfma_f32_16x16x32_bf16 v[36:39], v[88:91], v[100:103], v[36:39]
	v_mfma_f32_16x16x32_bf16 v[44:47], v[92:95], v[100:103], v[44:47]
	v_mfma_f32_16x16x32_bf16 v[32:35], v[80:83], v[104:107], v[32:35]
	v_mfma_f32_16x16x32_bf16 v[28:31], v[84:87], v[104:107], v[28:31]
	v_mfma_f32_16x16x32_bf16 v[24:27], v[88:91], v[104:107], v[24:27]
	v_mfma_f32_16x16x32_bf16 v[20:23], v[92:95], v[104:107], v[20:23]
	v_mfma_f32_16x16x32_bf16 v[16:19], v[80:83], v[108:111], v[16:19]
	v_mfma_f32_16x16x32_bf16 v[12:15], v[84:87], v[108:111], v[12:15]
	v_mfma_f32_16x16x32_bf16 v[8:11], v[88:91], v[108:111], v[8:11]
	v_mfma_f32_16x16x32_bf16 v[4:7], v[92:95], v[108:111], v[4:7]
	v_or_b32_e32 v112, s100, v77
	v_add_u32_e32 v113, v112, v78
	v_add_u32_e32 v112, v112, v79
	ds_read_b128 v[80:83], v113 offset:16384
	ds_read_b128 v[84:87], v113 offset:17408
	ds_read_b128 v[88:91], v113 offset:18432
	ds_read_b128 v[92:95], v113 offset:19456
	ds_read_b128 v[96:99], v112
	ds_read_b128 v[100:103], v112 offset:1024
	ds_read_b128 v[104:107], v112 offset:2048
	ds_read_b128 v[108:111], v112 offset:3072
	s_add_i32 s100, s100, 0x6000
	s_cmp_eq_u32 s100, 0x12000
	s_cselect_b32 s100, 0, s100
	s_mov_b32 s1, s6
	s_branch .Lpp_B_3
.Lpp_lastB_3:
	v_mfma_f32_16x16x32_bf16 v[64:67], v[80:83], v[96:99], v[64:67]
	v_mfma_f32_16x16x32_bf16 v[60:63], v[84:87], v[96:99], v[60:63]
	v_mfma_f32_16x16x32_bf16 v[56:59], v[88:91], v[96:99], v[56:59]
	v_mfma_f32_16x16x32_bf16 v[52:55], v[92:95], v[96:99], v[52:55]
	v_mfma_f32_16x16x32_bf16 v[48:51], v[80:83], v[100:103], v[48:51]
	v_mfma_f32_16x16x32_bf16 v[40:43], v[84:87], v[100:103], v[40:43]
	v_mfma_f32_16x16x32_bf16 v[36:39], v[88:91], v[100:103], v[36:39]
	v_mfma_f32_16x16x32_bf16 v[44:47], v[92:95], v[100:103], v[44:47]
	v_mfma_f32_16x16x32_bf16 v[32:35], v[80:83], v[104:107], v[32:35]
	v_mfma_f32_16x16x32_bf16 v[28:31], v[84:87], v[104:107], v[28:31]
	v_mfma_f32_16x16x32_bf16 v[24:27], v[88:91], v[104:107], v[24:27]
	v_mfma_f32_16x16x32_bf16 v[20:23], v[92:95], v[104:107], v[20:23]
	v_mfma_f32_16x16x32_bf16 v[16:19], v[80:83], v[108:111], v[16:19]
	v_mfma_f32_16x16x32_bf16 v[12:15], v[84:87], v[108:111], v[12:15]
	v_mfma_f32_16x16x32_bf16 v[8:11], v[88:91], v[108:111], v[8:11]
	v_mfma_f32_16x16x32_bf16 v[4:7], v[92:95], v[108:111], v[4:7]
	s_mov_b32 s1, s6
; template <int MODE, bool SWAP, int MT>
; DI void gemm_tile(const int wv_, const Params& p, const u16* __restrict__ A, const u16* __restrict__ Bt, int brow, int bcol, char* smem, const float* gnext) {
;     ...
;   for (int t = 0; t < 32; ++t) {
;     asm volatile("s_waitcnt vmcnt(0)" ::: "memory");
;     __syncthreads();
;     if (t + 1 < 32) stage(t + 1, (t + 1) & 1);
;     const char* sA = smem + (t & 1) * 24576; const char* sB = sA + 16384;
;     bf16x8 Af[MT], Bf[4];
; #pragma unroll
;     for (int n = 0; n < 4; ++n) Bf[n] = *(const bf16x8*)(sB + (wc * 64 + n * 16 + fr) * 64 + fq * 16);
;     constexpr int MH = MT >= 2 ? MT / 2 : 1;
; #pragma unroll
;     for (int m = 0; m < MH; ++m) Af[m] = *(const bf16x8*)(sA + (wr * (16 * MT) + m * 16 + fr) * 64 + fq * 16);
;     __builtin_amdgcn_sched_barrier(0);
; #pragma unroll
;     for (int m = MH; m < MT; ++m) Af[m] = *(const bf16x8*)(sA + (wr * (16 * MT) + m * 16 + fr) * 64 + fq * 16);
; #pragma unroll
;     for (int m = 0; m < MH; ++m)
; #pragma unroll
;       for (int n = 0; n < 4; ++n)
;         acc[m][n] = SWAP ? __builtin_amdgcn_mfma_f32_16x16x32_bf16(Bf[n], Af[m], acc[m][n], 0, 0, 0)
;                          : __builtin_amdgcn_mfma_f32_16x16x32_bf16(Af[m], Bf[n], acc[m][n], 0, 0, 0);
;     __builtin_amdgcn_sched_barrier(0);
; #pragma unroll
;     for (int m = MH; m < MT; ++m)
; #pragma unroll
;       for (int n = 0; n < 4; ++n)
;         acc[m][n] = SWAP ? __builtin_amdgcn_mfma_f32_16x16x32_bf16(Bf[n], Af[m], acc[m][n], 0, 0, 0)
;                          : __builtin_amdgcn_mfma_f32_16x16x32_bf16(Af[m], Bf[n], acc[m][n], 0, 0, 0);
;   }
;     ...
;         const float rs = rowscale(p.ss, R);
; #pragma unroll
;         for (int n = 0; n < 4; ++n) { acc[m][n][0] *= rs; acc[m][n][1] *= rs; acc[m][n][2] *= rs; acc[m][n][3] *= rs; }
;         if (MODE == 0 && bcol >= 512 && bcol < 1536) {
;           int b = R / P, pos = R - b * P;
;           u16* dstb = (bcol < 1024 ? p.kc : p.vc);
; #pragma unroll
;           for (int n = 0; n < 4; ++n) {
;             int cc = (bcol & 511) + wc * 64 + n * 16 + fq * 4;
;             uint2 o; o.x = pack2(acc[m][n][0], acc[m][n][1]); o.y = pack2(acc[m][n][2], acc[m][n][3]);
;             *(uint2*)(dstb + ((size_t)((b * 8 + (cc >> 6)) * P + pos)) * 64 + (cc & 63)) = o;
;           }
;         } else {
;           const int LD = MODE == 0 ? LD_AB : LD_CD;
.Lpp_exit_3:
	v_add_u32_e32 v0, v77, v79
	v_add_u32_e32 v1, v77, v78
	s_waitcnt vmcnt(0)
	s_waitcnt vmcnt(0)
	s_barrier
	ds_read_b128 v[68:71], v0 offset:25600
	ds_read_b128 v[80:83], v0 offset:24576
	ds_read_b128 v[76:79], v1 offset:44032
	ds_read_b128 v[84:87], v1 offset:43008
	ds_read_b128 v[88:91], v1 offset:41984
	ds_read_b128 v[92:95], v1 offset:40960
	s_waitcnt lgkmcnt(0)
	v_mfma_f32_16x16x32_bf16 v[64:67], v[92:95], v[80:83], v[64:67]
	v_mfma_f32_16x16x32_bf16 v[60:63], v[88:91], v[80:83], v[60:63]
	v_mfma_f32_16x16x32_bf16 v[56:59], v[84:87], v[80:83], v[56:59]
	v_mfma_f32_16x16x32_bf16 v[52:55], v[76:79], v[80:83], v[52:55]
	ds_read_b128 v[80:83], v0 offset:26624
	ds_read_b128 v[96:99], v0 offset:27648
	v_mfma_f32_16x16x32_bf16 v[48:51], v[92:95], v[68:71], v[48:51]
	v_mfma_f32_16x16x32_bf16 v[40:43], v[88:91], v[68:71], v[40:43]
	v_mfma_f32_16x16x32_bf16 v[36:39], v[84:87], v[68:71], v[36:39]
	v_mfma_f32_16x16x32_bf16 v[44:47], v[76:79], v[68:71], v[44:47]
	v_or_b32_e32 v0, s0, v75
	v_lshl_add_u32 v68, v74, 6, v0
	v_ashrrev_i32_e32 v69, 31, v68
	v_lshlrev_b64 v[70:71], 6, v[68:69]
	v_lshl_add_u64 v[74:75], s[90:91], 0, v[70:71]
	s_waitcnt lgkmcnt(1)
	v_mfma_f32_16x16x32_bf16 v[32:35], v[92:95], v[80:83], v[32:35]
	s_waitcnt lgkmcnt(0)
	s_barrier
	v_mfma_f32_16x16x32_bf16 v[28:31], v[88:91], v[80:83], v[28:31]
	v_lshlrev_b32_e32 v2, 2, v73
	s_add_i32 s0, s23, 0xfffffe00
	s_cmpk_gt_u32 s0, 0x3ff
	v_mfma_f32_16x16x32_bf16 v[24:27], v[84:87], v[80:83], v[24:27]
	s_cselect_b64 s[8:9], -1, 0
	s_cmpk_lt_u32 s23, 0x400
	s_movk_i32 s0, 0x1058
	v_mfma_f32_16x16x32_bf16 v[20:23], v[76:79], v[80:83], v[20:23]
	s_cselect_b64 s[6:7], -1, 0
	s_mov_b64 s[10:11], -1
	v_mfma_f32_16x16x32_bf16 v[12:15], v[88:91], v[96:99], v[12:15]
	v_mfma_f32_16x16x32_bf16 v[8:11], v[84:87], v[96:99], v[8:11]
	v_mfma_f32_16x16x32_bf16 v[4:7], v[76:79], v[96:99], v[4:7]
	v_lshlrev_b32_e32 v77, 6, v72
	global_load_dwordx4 v[70:73], v[74:75], off offset:32
	global_load_dwordx4 v[78:81], v[74:75], off offset:16
	global_load_dwordx4 v[82:85], v[74:75], off
	global_load_dwordx4 v[86:89], v[74:75], off offset:48
	v_or_b32_e32 v76, s23, v77
	v_mfma_f32_16x16x32_bf16 v[16:19], v[92:95], v[96:99], v[16:19]
	v_or_b32_e32 v0, v76, v2
	v_cmp_gt_i32_e64 s[0:1], s0, v0
	s_waitcnt vmcnt(2)
	v_mov_b32_e32 v90, v79
	s_waitcnt vmcnt(1)
	v_mov_b32_e32 v74, v83
	v_mov_b32_e32 v75, v84
	v_mov_b32_e32 v91, v80
	v_mov_b32_e32 v83, v85
	v_mov_b32_e32 v79, v81
	v_mov_b32_e32 v80, v71
	v_pk_add_f32 v[74:75], v[74:75], v[82:83]
	v_pk_add_f32 v[78:79], v[90:91], v[78:79]
	v_pk_add_f32 v[70:71], v[70:71], v[80:81]
	v_mov_b32_e32 v80, v73
	v_pk_add_f32 v[74:75], v[74:75], v[74:75] op_sel:[0,1] op_sel_hi:[1,0]
	v_pk_add_f32 v[78:79], v[78:79], v[78:79] op_sel:[0,1] op_sel_hi:[1,0]
	v_pk_add_f32 v[72:73], v[72:73], v[80:81]
	s_waitcnt vmcnt(0)
	v_mov_b32_e32 v75, v86
	v_mov_b32_e32 v79, v87
	v_mov_b32_e32 v71, v88
	v_mov_b32_e32 v73, v89
	v_pk_add_f32 v[74:75], v[74:75], v[78:79]
	v_pk_add_f32 v[70:71], v[70:71], v[72:73]
	s_nop 0
	v_pk_add_f32 v[70:71], v[74:75], v[70:71]
	s_nop 0
	v_add_f32_e32 v1, v70, v71
	v_mov_b32_e32 v70, 0x358637bd
	v_fmamk_f32 v1, v1, 0x3a800000, v70
	v_cmp_gt_f32_e32 vcc, s96, v1
	v_mul_f32_e32 v70, 0x4b800000, v1
	s_nop 0
	v_cndmask_b32_e32 v1, v1, v70, vcc
	v_rsq_f32_e32 v1, v1
	s_nop 0
	v_mul_f32_e32 v70, 0x45800000, v1
	v_cndmask_b32_e32 v72, v1, v70, vcc
	v_pk_mul_f32 v[70:71], v[64:65], v[72:73] op_sel_hi:[1,0]
	v_pk_mul_f32 v[66:67], v[66:67], v[72:73] op_sel_hi:[1,0]
	v_pk_mul_f32 v[64:65], v[60:61], v[72:73] op_sel_hi:[1,0]
	v_pk_mul_f32 v[62:63], v[62:63], v[72:73] op_sel_hi:[1,0]
	v_pk_mul_f32 v[60:61], v[56:57], v[72:73] op_sel_hi:[1,0]
	v_pk_mul_f32 v[58:59], v[58:59], v[72:73] op_sel_hi:[1,0]
	v_pk_mul_f32 v[56:57], v[52:53], v[72:73] op_sel_hi:[1,0]
	v_pk_mul_f32 v[52:53], v[54:55], v[72:73] op_sel_hi:[1,0]
	s_and_b64 vcc, exec, s[8:9]
	s_cbranch_vccz .LBB0_388
	v_mov_b64_e32 v[54:55], s[68:69]
	v_mad_i64_i32 v[72:73], s[10:11], v68, s35, v[54:55]
	v_lshlrev_b64 v[54:55], 7, v[68:69]
	s_and_saveexec_b64 s[10:11], s[0:1]
	s_cbranch_execz .LBB0_378
	s_movk_i32 s0, 0x5ff
	v_add_u32_e32 v1, 0xfffffc00, v0
	v_cmp_lt_i32_e32 vcc, s0, v0
	s_movk_i32 s0, 0xa00
	v_cvt_pk_bf16_f32 v74, v70, v71
	v_cndmask_b32_e32 v78, v0, v1, vcc
	v_ashrrev_i32_e32 v79, 31, v78
	v_cvt_pk_bf16_f32 v75, v66, v67
	v_lshl_add_u64 v[78:79], v[78:79], 1, v[72:73]
	v_cmp_eq_u32_e32 vcc, s0, v76
	global_store_dwordx2 v[78:79], v[74:75], off
	s_and_b64 exec, exec, vcc
	s_cbranch_execz .LBB0_378
	v_lshl_add_u64 v[78:79], s[78:79], 0, v[54:55]
	v_mov_b32_e32 v1, v3
	v_lshl_add_u64 v[78:79], v[0:1], 1, v[78:79]
	v_add_co_u32_e32 v78, vcc, 0xfffff000, v78
	s_nop 1
	v_addc_co_u32_e32 v79, vcc, -1, v79, vcc
	global_store_dwordx2 v[78:79], v[74:75], off offset:-1024

; template <int MODE, bool SWAP, int MT>
; DI void gemm_tile(const int wv_, const Params& p, const u16* __restrict__ A, const u16* __restrict__ Bt, int brow, int bcol, char* smem, const float* gnext) {
;     ...
;   const int tid = tid_, wid = tid >> 6, lane = tid & 63, wr = wid >> 1, wc = wid & 1, fr = lane & 15, fq = lane >> 4;
;   f32x4 acc[MT][4];
; #pragma unroll
;   for (int m = 0; m < MT; ++m)
; #pragma unroll
;     for (int n = 0; n < 4; ++n) acc[m][n] = f32x4{0.f, 0.f, 0.f, 0.f};
;   const int ra = tid >> 2, cb = (tid & 3) * 8;
;   const u16* ga0 = A + (size_t)(brow + ra) * 1024 + cb;
;   const u16* ga1 = A + (size_t)(brow + 128 + ra) * 1024 + cb;
;   const u16* gb0 = Bt + (size_t)(bcol + ra) * 1024 + cb;
;   auto stage = [&](int t, int buf) {
;     char* sA = smem + buf * 24576; char* sB = sA + 16384;
;     if (MT >= 2 || tid < 256) __builtin_amdgcn_global_load_lds((const unsigned*)(ga0 + t * 32), (unsigned*)(sA + tid * 16), 16, 0, 0);
;     if (MT == 4) __builtin_amdgcn_global_load_lds((const unsigned*)(ga1 + t * 32), (unsigned*)(sA + 8192 + tid * 16), 16, 0, 0);
;     __builtin_amdgcn_global_load_lds((const unsigned*)(gb0 + t * 32), (unsigned*)(sB + tid * 16), 16, 0, 0);
;   };
;   stage(0, 0);
;   for (int t = 0; t < 32; ++t) {
;     asm volatile("s_waitcnt vmcnt(0)" ::: "memory");
;     __syncthreads();
;     if (t + 1 < 32) stage(t + 1, (t + 1) & 1);
;     const char* sA = smem + (t & 1) * 24576; const char* sB = sA + 16384;
;     bf16x8 Af[MT], Bf[4];
; #pragma unroll
;     for (int n = 0; n < 4; ++n) Bf[n] = *(const bf16x8*)(sB + (wc * 64 + n * 16 + fr) * 64 + fq * 16);
;     constexpr int MH = MT >= 2 ? MT / 2 : 1;
; #pragma unroll
;     for (int m = 0; m < MH; ++m) Af[m] = *(const bf16x8*)(sA + (wr * (16 * MT) + m * 16 + fr) * 64 + fq * 16);
; template <int MODE>
; DI void phase_gemm(const int wv_, const Params& p, const u16* A, const u16* Bt, int NT, char* smem, const float* gnext) {
;     ...
;     int tm = tile / NT, tn = tile - tm * NT;
;     if (MODE == 1 && tn >= 20 && tn < 24) gemm_tile<1, false, 4>(wv_, p, A, Bt, tm * 256, tn * 128, smem, gnext);
;     else gemm_tile<MODE, true, 4>(wv_, p, A, Bt, tm * 256, tn * 128, smem, gnext);
.LBB0_828:
	s_ashr_i32 s0, s28, 31
	s_mov_b32 s3, 0
	s_lshr_b32 s0, s0, 29
	s_add_i32 s0, s28, s0
	v_mbcnt_lo_u32_b32 v0, -1, s3
	v_mbcnt_hi_u32_b32 v0, -1, v0
	s_ashr_i32 s1, s0, 3
	v_add_u32_e32 v77, s33, v0
	s_lshl_b32 s0, s1, 8
	s_mov_b32 s3, s16
	v_ashrrev_i32_e32 v12, 2, v77
	v_add_u32_e32 v0, s0, v12
	s_mov_b32 s3, s17
	s_waitcnt lgkmcnt(0)
	v_ashrrev_i32_e32 v1, 31, v0
	v_lshlrev_b64 v[4:5], 11, v[0:1]
	v_lshlrev_b32_e32 v74, 4, v77
	v_lshl_add_u64 v[6:7], s[50:51], 0, v[4:5]
	v_and_b32_e32 v2, 48, v74
	v_add_u32_e32 v0, 0x80, v0
	v_readfirstlane_b32 s3, v74
	s_lshl_b32 s2, s1, 10
	s_lshl_b32 s1, s28, 7
	v_lshl_add_u64 v[6:7], v[6:7], 0, v[2:3]
	v_ashrrev_i32_e32 v1, 31, v0
	s_mov_b32 m0, s3
	s_sub_i32 s12, s1, s2
	v_lshlrev_b64 v[8:9], 11, v[0:1]
	global_load_lds_dwordx4 v[6:7], off
	v_add_u32_e32 v6, 0x2000, v74
	v_lshl_add_u64 v[0:1], s[50:51], 0, v[8:9]
	v_add_u32_e32 v10, s12, v12
	v_readfirstlane_b32 s3, v6
	v_lshl_add_u64 v[0:1], v[0:1], 0, v[2:3]
	v_ashrrev_i32_e32 v11, 31, v10
	s_mov_b32 m0, s3
	v_lshlrev_b64 v[10:11], 11, v[10:11]
	global_load_lds_dwordx4 v[0:1], off
	v_add_u32_e32 v0, 0x4000, v74
	v_lshl_add_u64 v[10:11], s[6:7], 0, v[10:11]
	v_readfirstlane_b32 s3, v0
	v_lshl_add_u64 v[10:11], v[10:11], 0, v[2:3]
	s_mov_b32 m0, s3
	v_and_b32_e32 v73, 15, v77
	global_load_lds_dwordx4 v[10:11], off
	v_readlane_b32 s4, v127, 28
	v_bfe_u32 v76, v77, 6, 1
	v_ashrrev_i32_e32 v72, 7, v77
	v_lshlrev_b32_e32 v0, 6, v73
	v_or_b32_e32 v4, v4, v2
	v_readlane_b32 s5, v127, 29
	v_lshl_or_b32 v78, v76, 12, v0
	v_lshl_or_b32 v79, v72, 12, v0
	v_lshl_add_u64 v[0:1], s[4:5], 0, v[4:5]
	v_add_u32_e32 v4, s23, v12
	v_subrev_u32_e32 v4, s2, v4
	v_ashrrev_i32_e32 v5, 31, v4
	v_lshlrev_b64 v[4:5], 11, v[4:5]
	v_readlane_b32 s2, v127, 30
	v_or_b32_e32 v4, v4, v2
	v_readlane_b32 s3, v127, 31
	v_or_b32_e32 v8, v8, v2
	s_mov_b32 s1, 0
	v_lshl_add_u64 v[70:71], s[2:3], 0, v[4:5]
	v_mov_b32_e32 v4, 0
	v_and_b32_e32 v75, 48, v77
	v_lshl_add_u64 v[68:69], s[4:5], 0, v[8:9]
	v_mov_b32_e32 v5, v4
	v_mov_b32_e32 v6, v4
	v_mov_b32_e32 v7, v4
	v_mov_b32_e32 v8, v4
	v_mov_b32_e32 v9, v4
	v_mov_b32_e32 v10, v4
	v_mov_b32_e32 v11, v4
	v_mov_b32_e32 v12, v4
	v_mov_b32_e32 v13, v4
	v_mov_b32_e32 v14, v4
	v_mov_b32_e32 v15, v4
	v_mov_b32_e32 v16, v4
	v_mov_b32_e32 v17, v4
	v_mov_b32_e32 v18, v4
	v_mov_b32_e32 v19, v4
	v_mov_b32_e32 v20, v4
	v_mov_b32_e32 v21, v4
	v_mov_b32_e32 v22, v4
	v_mov_b32_e32 v23, v4
	v_mov_b32_e32 v24, v4
	v_mov_b32_e32 v25, v4
	v_mov_b32_e32 v26, v4
	v_mov_b32_e32 v27, v4
	v_mov_b32_e32 v28, v4
	v_mov_b32_e32 v29, v4
	v_mov_b32_e32 v30, v4
	v_mov_b32_e32 v31, v4
	v_mov_b32_e32 v32, v4
	v_mov_b32_e32 v33, v4
	v_mov_b32_e32 v34, v4
	v_mov_b32_e32 v35, v4
	v_mov_b32_e32 v36, v4
	v_mov_b32_e32 v37, v4
	v_mov_b32_e32 v38, v4
	v_mov_b32_e32 v39, v4
	v_mov_b32_e32 v40, v4
	v_mov_b32_e32 v41, v4
	v_mov_b32_e32 v42, v4
	v_mov_b32_e32 v43, v4
	v_mov_b32_e32 v44, v4
	v_mov_b32_e32 v45, v4
	v_mov_b32_e32 v46, v4
	v_mov_b32_e32 v47, v4
	v_mov_b32_e32 v48, v4
	v_mov_b32_e32 v49, v4
	v_mov_b32_e32 v50, v4
	v_mov_b32_e32 v51, v4
	v_mov_b32_e32 v52, v4
	v_mov_b32_e32 v53, v4
	v_mov_b32_e32 v54, v4
	v_mov_b32_e32 v55, v4
	v_mov_b32_e32 v56, v4
	v_mov_b32_e32 v57, v4
	v_mov_b32_e32 v58, v4
	v_mov_b32_e32 v59, v4
	v_mov_b32_e32 v60, v4
	v_mov_b32_e32 v61, v4
	v_mov_b32_e32 v62, v4
	v_mov_b32_e32 v63, v4
	v_mov_b32_e32 v64, v4
	v_mov_b32_e32 v65, v4
	v_mov_b32_e32 v66, v4
	v_mov_b32_e32 v67, v4
	v_readfirstlane_b32 s98, v74
	s_movk_i32 s99, 0x6000
	s_add_i32 s101, s98, s99
	s_mov_b32 m0, s101
	s_add_i32 s101, s101, 0x2000
	global_load_lds_dwordx4 v[0:1], off
	s_mov_b32 m0, s101
	s_add_i32 s101, s101, 0x2000
	global_load_lds_dwordx4 v[68:69], off
	s_mov_b32 m0, s101
	s_add_i32 s99, s99, 0x6000
	global_load_lds_dwordx4 v[70:71], off
	s_cmp_eq_u32 s99, 0x12000
	s_cselect_b32 s99, 0, s99
	v_lshl_add_u64 v[0:1], v[0:1], 0, 64
	v_lshl_add_u64 v[68:69], v[68:69], 0, 64
	v_lshl_add_u64 v[70:71], v[70:71], 0, 64
	s_add_i32 s101, s98, s99
	s_mov_b32 m0, s101
	s_add_i32 s101, s101, 0x2000
	global_load_lds_dwordx4 v[0:1], off
	s_mov_b32 m0, s101
	s_add_i32 s101, s101, 0x2000
	global_load_lds_dwordx4 v[68:69], off
	s_mov_b32 m0, s101
	s_add_i32 s99, s99, 0x6000
	global_load_lds_dwordx4 v[70:71], off
	s_cmp_eq_u32 s99, 0x12000
	s_cselect_b32 s99, 0, s99
	v_lshl_add_u64 v[0:1], v[0:1], 0, 64
	v_lshl_add_u64 v[68:69], v[68:69], 0, 64
	v_lshl_add_u64 v[70:71], v[70:71], 0, 64
	s_mov_b32 s100, 0
	s_waitcnt vmcnt(6)
	s_barrier
	v_or_b32_e32 v112, s100, v75
	v_add_u32_e32 v113, v112, v78
	v_add_u32_e32 v112, v112, v79
	ds_read_b128 v[80:83], v113 offset:16384
	ds_read_b128 v[84:87], v113 offset:17408
	ds_read_b128 v[88:91], v113 offset:18432
	ds_read_b128 v[92:95], v113 offset:19456
	ds_read_b128 v[96:99], v112
	ds_read_b128 v[100:103], v112 offset:1024
	ds_read_b128 v[104:107], v112 offset:2048
	ds_read_b128 v[108:111], v112 offset:3072
	s_add_i32 s100, s100, 0x6000
	s_cmp_eq_u32 s100, 0x12000
	s_cselect_b32 s100, 0, s100
	s_cmp_ge_u32 s33, 0x100
	s_cbranch_scc1 .Lpp_B_4

; template <int MODE, bool SWAP, int MT>
; DI void gemm_tile(const int wv_, const Params& p, const u16* __restrict__ A, const u16* __restrict__ Bt, int brow, int bcol, char* smem, const float* gnext) {
;     ...
;   for (int t = 0; t < 32; ++t) {
;     asm volatile("s_waitcnt vmcnt(0)" ::: "memory");
;     __syncthreads();
;     if (t + 1 < 32) stage(t + 1, (t + 1) & 1);
;     const char* sA = smem + (t & 1) * 24576; const char* sB = sA + 16384;
;     bf16x8 Af[MT], Bf[4];
; #pragma unroll
;     for (int n = 0; n < 4; ++n) Bf[n] = *(const bf16x8*)(sB + (wc * 64 + n * 16 + fr) * 64 + fq * 16);
;     constexpr int MH = MT >= 2 ? MT / 2 : 1;
; #pragma unroll
;     for (int m = 0; m < MH; ++m) Af[m] = *(const bf16x8*)(sA + (wr * (16 * MT) + m * 16 + fr) * 64 + fq * 16);
;     __builtin_amdgcn_sched_barrier(0);
; #pragma unroll
;     for (int m = MH; m < MT; ++m) Af[m] = *(const bf16x8*)(sA + (wr * (16 * MT) + m * 16 + fr) * 64 + fq * 16);
; #pragma unroll
;     for (int m = 0; m < MH; ++m)
; #pragma unroll
;       for (int n = 0; n < 4; ++n)
;         acc[m][n] = SWAP ? __builtin_amdgcn_mfma_f32_16x16x32_bf16(Bf[n], Af[m], acc[m][n], 0, 0, 0)
;                          : __builtin_amdgcn_mfma_f32_16x16x32_bf16(Af[m], Bf[n], acc[m][n], 0, 0, 0);
;     __builtin_amdgcn_sched_barrier(0);
; #pragma unroll
;     for (int m = MH; m < MT; ++m)
; #pragma unroll
;       for (int n = 0; n < 4; ++n)
;         acc[m][n] = SWAP ? __builtin_amdgcn_mfma_f32_16x16x32_bf16(Bf[n], Af[m], acc[m][n], 0, 0, 0)
;                          : __builtin_amdgcn_mfma_f32_16x16x32_bf16(Af[m], Bf[n], acc[m][n], 0, 0, 0);
;   }
;     ...
;       int R = brow + wr * (16 * MT) + m * 16 + fr;
;       if (MODE == 2) {
;         int b = R / P, pos = R - b * P;
;         const bool valid = pos >= 112;
;         float* hr = valid ? hrow(p, b, pos) : nullptr;
;         float ssq = 0.f;
; #pragma unroll
;         for (int n = 0; n < 4; ++n) {
;           int col = bcol + wc * 64 + n * 16 + fq * 4;
;           float4 v = make_float4(0.f, 0.f, 0.f, 0.f);
;           if (valid) {
;             v = *(float4*)(hr + col);
;             v.x += acc[m][n][0]; v.y += acc[m][n][1]; v.z += acc[m][n][2]; v.w += acc[m][n][3];
;             *(float4*)(hr + col) = v;
.Lpp_last_4:
	v_mfma_f32_16x16x32_bf16 v[32:35], v[80:83], v[104:107], v[32:35]
	v_mfma_f32_16x16x32_bf16 v[28:31], v[84:87], v[104:107], v[28:31]
	v_mfma_f32_16x16x32_bf16 v[24:27], v[88:91], v[104:107], v[24:27]
	v_mfma_f32_16x16x32_bf16 v[20:23], v[92:95], v[104:107], v[20:23]
	v_mfma_f32_16x16x32_bf16 v[16:19], v[80:83], v[108:111], v[16:19]
	v_mfma_f32_16x16x32_bf16 v[12:15], v[84:87], v[108:111], v[12:15]
	v_mfma_f32_16x16x32_bf16 v[8:11], v[88:91], v[108:111], v[8:11]
	v_mfma_f32_16x16x32_bf16 v[4:7], v[92:95], v[108:111], v[4:7]
	s_mov_b32 s1, s2
	s_branch .Lpp_exit_4
.Lpp_B_4:
	s_add_i32 s2, s1, 1
	s_waitcnt lgkmcnt(0)
	s_cmp_gt_u32 s1, 29
	s_cbranch_scc1 .Lpp_lastB_4
	s_waitcnt vmcnt(3)
	s_barrier
	s_cmp_gt_u32 s1, 28
	s_cbranch_scc1 .Lpp_nodmaB_4
	s_add_i32 s101, s98, s99
	s_mov_b32 m0, s101
	s_add_i32 s101, s101, 0x2000
	global_load_lds_dwordx4 v[0:1], off
	s_mov_b32 m0, s101
	s_add_i32 s101, s101, 0x2000
	global_load_lds_dwordx4 v[68:69], off
	s_mov_b32 m0, s101
	s_add_i32 s99, s99, 0x6000
	global_load_lds_dwordx4 v[70:71], off
	s_cmp_eq_u32 s99, 0x12000
	s_cselect_b32 s99, 0, s99
	v_lshl_add_u64 v[0:1], v[0:1], 0, 64
	v_lshl_add_u64 v[68:69], v[68:69], 0, 64
	v_lshl_add_u64 v[70:71], v[70:71], 0, 64
.Lpp_nodmaB_4:
	v_mfma_f32_16x16x32_bf16 v[64:67], v[80:83], v[96:99], v[64:67]
	v_mfma_f32_16x16x32_bf16 v[60:63], v[84:87], v[96:99], v[60:63]
	v_mfma_f32_16x16x32_bf16 v[56:59], v[88:91], v[96:99], v[56:59]
	v_mfma_f32_16x16x32_bf16 v[52:55], v[92:95], v[96:99], v[52:55]
	v_mfma_f32_16x16x32_bf16 v[48:51], v[80:83], v[100:103], v[48:51]
	v_mfma_f32_16x16x32_bf16 v[44:47], v[84:87], v[100:103], v[44:47]
	v_mfma_f32_16x16x32_bf16 v[40:43], v[88:91], v[100:103], v[40:43]
	v_mfma_f32_16x16x32_bf16 v[36:39], v[92:95], v[100:103], v[36:39]
	v_mfma_f32_16x16x32_bf16 v[32:35], v[80:83], v[104:107], v[32:35]
	v_mfma_f32_16x16x32_bf16 v[28:31], v[84:87], v[104:107], v[28:31]
	v_mfma_f32_16x16x32_bf16 v[24:27], v[88:91], v[104:107], v[24:27]
	v_mfma_f32_16x16x32_bf16 v[20:23], v[92:95], v[104:107], v[20:23]
	v_mfma_f32_16x16x32_bf16 v[16:19], v[80:83], v[108:111], v[16:19]
	v_mfma_f32_16x16x32_bf16 v[12:15], v[84:87], v[108:111], v[12:15]
	v_mfma_f32_16x16x32_bf16 v[8:11], v[88:91], v[108:111], v[8:11]
	v_mfma_f32_16x16x32_bf16 v[4:7], v[92:95], v[108:111], v[4:7]
	v_or_b32_e32 v112, s100, v75
	v_add_u32_e32 v113, v112, v78
	v_add_u32_e32 v112, v112, v79
	ds_read_b128 v[80:83], v113 offset:16384
	ds_read_b128 v[84:87], v113 offset:17408
	ds_read_b128 v[88:91], v113 offset:18432
	ds_read_b128 v[92:95], v113 offset:19456
	ds_read_b128 v[96:99], v112
	ds_read_b128 v[100:103], v112 offset:1024
	ds_read_b128 v[104:107], v112 offset:2048
	ds_read_b128 v[108:111], v112 offset:3072
	s_add_i32 s100, s100, 0x6000
	s_cmp_eq_u32 s100, 0x12000
	s_cselect_b32 s100, 0, s100
	s_mov_b32 s1, s2
	s_branch .Lpp_B_4
.Lpp_lastB_4:
	v_mfma_f32_16x16x32_bf16 v[64:67], v[80:83], v[96:99], v[64:67]
	v_mfma_f32_16x16x32_bf16 v[60:63], v[84:87], v[96:99], v[60:63]
	v_mfma_f32_16x16x32_bf16 v[56:59], v[88:91], v[96:99], v[56:59]
	v_mfma_f32_16x16x32_bf16 v[52:55], v[92:95], v[96:99], v[52:55]
	v_mfma_f32_16x16x32_bf16 v[48:51], v[80:83], v[100:103], v[48:51]
	v_mfma_f32_16x16x32_bf16 v[44:47], v[84:87], v[100:103], v[44:47]
	v_mfma_f32_16x16x32_bf16 v[40:43], v[88:91], v[100:103], v[40:43]
	v_mfma_f32_16x16x32_bf16 v[36:39], v[92:95], v[100:103], v[36:39]
	v_mfma_f32_16x16x32_bf16 v[32:35], v[80:83], v[104:107], v[32:35]
	v_mfma_f32_16x16x32_bf16 v[28:31], v[84:87], v[104:107], v[28:31]
	v_mfma_f32_16x16x32_bf16 v[24:27], v[88:91], v[104:107], v[24:27]
	v_mfma_f32_16x16x32_bf16 v[20:23], v[92:95], v[104:107], v[20:23]
	v_mfma_f32_16x16x32_bf16 v[16:19], v[80:83], v[108:111], v[16:19]
	v_mfma_f32_16x16x32_bf16 v[12:15], v[84:87], v[108:111], v[12:15]
	v_mfma_f32_16x16x32_bf16 v[8:11], v[88:91], v[108:111], v[8:11]
	v_mfma_f32_16x16x32_bf16 v[4:7], v[92:95], v[108:111], v[4:7]
	s_mov_b32 s1, s2
.Lpp_exit_4:
	v_add_u32_e32 v0, v75, v79
	v_add_u32_e32 v1, v75, v78
	s_waitcnt vmcnt(0)
	s_waitcnt vmcnt(0)
	s_barrier
	ds_read_b128 v[80:83], v0 offset:25600
	ds_read_b128 v[84:87], v0 offset:24576
	ds_read_b128 v[88:91], v1 offset:44032
	ds_read_b128 v[92:95], v1 offset:43008
	ds_read_b128 v[96:99], v1 offset:41984
	ds_read_b128 v[100:103], v1 offset:40960
	s_waitcnt lgkmcnt(0)
	v_mfma_f32_16x16x32_bf16 v[68:71], v[100:103], v[84:87], v[64:67]
	v_mfma_f32_16x16x32_bf16 v[60:63], v[96:99], v[84:87], v[60:63]
	v_mfma_f32_16x16x32_bf16 v[56:59], v[92:95], v[84:87], v[56:59]
	v_mfma_f32_16x16x32_bf16 v[52:55], v[88:91], v[84:87], v[52:55]
	ds_read_b128 v[64:67], v0 offset:26624
	ds_read_b128 v[84:87], v0 offset:27648
	v_mfma_f32_16x16x32_bf16 v[48:51], v[100:103], v[80:83], v[48:51]
	v_mfma_f32_16x16x32_bf16 v[44:47], v[96:99], v[80:83], v[44:47]
	v_mfma_f32_16x16x32_bf16 v[40:43], v[92:95], v[80:83], v[40:43]
	v_mfma_f32_16x16x32_bf16 v[36:39], v[88:91], v[80:83], v[36:39]
	v_or_b32_e32 v0, s0, v73
	v_lshl_add_u32 v72, v72, 6, v0
	s_mov_b32 s0, 0x7e07e07f
	v_mul_hi_i32 v0, v72, s0
	s_waitcnt lgkmcnt(1)
	v_mfma_f32_16x16x32_bf16 v[32:35], v[100:103], v[64:67], v[32:35]
	v_lshrrev_b32_e32 v1, 31, v0
	v_ashrrev_i32_e32 v0, 12, v0
	v_add_u32_e32 v0, v0, v1
	v_mfma_f32_16x16x32_bf16 v[28:31], v[96:99], v[64:67], v[28:31]
	s_movk_i32 s0, 0xdf80
	v_mad_i32_i24 v1, v0, s0, v72
	v_cmp_lt_i32_e64 s[2:3], s54, v1
	v_mfma_f32_16x16x32_bf16 v[24:27], v[92:95], v[64:67], v[24:27]
	v_mov_b64_e32 v[74:75], 0
	s_waitcnt lgkmcnt(0)
	s_barrier
	v_mfma_f32_16x16x32_bf16 v[20:23], v[88:91], v[64:67], v[20:23]
	v_mfma_f32_16x16x32_bf16 v[16:19], v[100:103], v[84:87], v[16:19]
	v_mfma_f32_16x16x32_bf16 v[12:15], v[96:99], v[84:87], v[12:15]
	v_mfma_f32_16x16x32_bf16 v[8:11], v[92:95], v[84:87], v[8:11]
	v_mfma_f32_16x16x32_bf16 v[4:7], v[88:91], v[84:87], v[4:7]
	s_and_saveexec_b64 s[0:1], s[2:3]
	s_cbranch_execz .LBB0_832
	s_movk_i32 s4, 0x7f
	v_cmp_lt_u32_e32 vcc, s4, v1
	v_mov_b32_e32 v64, 0xffffff90
	v_mov_b32_e32 v65, 0xffffff80
	v_cndmask_b32_e64 v2, 4, 13, vcc
	v_cndmask_b32_e32 v66, v64, v65, vcc
	v_lshlrev_b32_e32 v0, v2, v0
	v_mov_b32_e32 v64, s85
	v_mov_b32_e32 v65, s43
	v_add3_u32 v0, v66, v1, v0
	v_cndmask_b32_e32 v65, v64, v65, vcc
	v_mov_b32_e32 v64, s84
	v_mov_b32_e32 v67, s42
	v_ashrrev_i32_e32 v1, 31, v0
	v_cndmask_b32_e32 v64, v64, v67, vcc
	v_lshlrev_b64 v[0:1], 12, v[0:1]
	v_lshl_add_u64 v[74:75], v[64:65], 0, v[0:1]
